# scan and attention split across workgroups: 128 workgroups scan two row groups each (two consumer waves, K=32-merged consumer MFMAs, LDS prefetch), 128 workgroups do attention (4 items each, throttled
# speedup vs baseline: 1.0090x; 1.0090x over previous
; #define LAS __attribute__((address_space(3)))
; __device__ __forceinline__ int otid() { int t = threadIdx.x; asm volatile("" : "+v"(t)); return t; }
; __device__ __forceinline__ int obid() { int b = blockIdx.x; asm volatile("" : "+s"(b)); return b; }
; __device__ __forceinline__ void phase_scan2(const Params& p, int l, LAS unsigned char* lds) {
;     unsigned char* R = p.ws + WS_R;
;     const bf16_t* Rb = (const bf16_t*)(R + R_R); const bf16_t* Kb = (const bf16_t*)(R + R_K); const bf16_t* Vb = (const bf16_t*)(R + (l == 0 ? R_V : R_VNEW));
;     const bf16_t* Ab = (const bf16_t*)(R + R_A); const _Float16* EW = (const _Float16*)(R + R_EW);
;     bf16_t* Y = (bf16_t*)(R + R_Y); float* CB = (float*)(R + R_CB);
;     const float* k_k = p.in[15] + (size_t)l * 512; const float* k_a = p.in[16] + (size_t)l * 512; const float* r_k = p.in[17] + (size_t)l * 512;
;     const int tid = otid(), wid = tid >> 6, lane = tid & 63, fr = lane & 15, fq = lane >> 4;
;     constexpr int NCH = SEQ / 16, NRD = (NCH + SC_NP - 1) / SC_NP;
;     for (int job = obid(); job < 256; job += gridDim.x) {
;         const int bh = job >> 2, rg = job & 3, b = bh >> 3, h = bh & 7;
;         const size_t tok0 = (size_t)b * SEQ;
;         const int pw = wid - 3, j = lane;
;         const float kkc = k_k[h * 64 + j], kac = k_a[h * 64 + j], rkc = r_k[h * 64 + j];
.Lsc_entry:
	v_lshrrev_b32_e32 v4, 6, v183
	s_add_u32 s26, s74, 0xc000000
	v_and_b32_e32 v1, 15, v183
	v_readfirstlane_b32 s25, v4
	s_addc_u32 s27, s75, 0
	s_add_u32 s36, s74, 0x13000000
	v_bfe_u32 v2, v183, 4, 2
	v_lshrrev_b32_e32 v4, 2, v1
	v_and_b32_e32 v7, 3, v1
	s_addc_u32 s37, s75, 0
	s_add_u32 s38, s74, 0xa000000
	v_lshlrev_b32_e32 v6, 5, v1
	v_lshl_add_u32 v4, v2, 2, v4
	v_lshlrev_b32_e32 v7, 3, v7
	s_addc_u32 s39, s75, 0
	s_add_u32 s46, s74, 0x11000000
	s_mov_b32 s13, s5
	v_and_b32_e32 v0, 63, v183
	v_lshl_add_u32 v6, v2, 3, v6
	v_lshl_add_u32 v7, v4, 5, v7
	s_addc_u32 s47, s75, 0
	s_cmp_ge_u32 s13, 128
	s_cbranch_scc1 .Lsc_exit
.Lsc_job:
	s_lshr_b32 s0, s13, 1
	s_and_b32 s53, s13, 1
	s_lshl_b32 s53, s53, 1
	s_lshr_b32 s54, s0, 3
	s_and_b32 s52, s0, 7
	s_cmp_eq_u32 s25, 0
	s_cbranch_scc1 .Lsc_consumer
	s_cmp_eq_u32 s25, 4
	s_cbranch_scc1 .Lsc_consumer

; #define LAS __attribute__((address_space(3)))
; __device__ __forceinline__ float bf2f(bf16_t b) { return __uint_as_float(((unsigned)b) << 16); }
; __device__ __forceinline__ bf16_t bf1(float x) { return (bf16_t)(pk_bf16(x, 0.f) & 0xffffu); }
; __device__ __forceinline__ void phase_scan2(const Params& p, int l, LAS unsigned char* lds) {
;     ...
;         const float kkc = k_k[h * 64 + j], kac = k_a[h * 64 + j], rkc = r_k[h * 64 + j];
;         unsigned short kraw[16], araw[16], rraw[16]; _Float16 eraw[16]; unsigned short vraw[4];
; #pragma unroll
;         for (int t = 0; t < 16; ++t) { kraw[t] = 0; araw[t] = 0; rraw[t] = 0; eraw[t] = (_Float16)0; }
; #pragma unroll
;         for (int q = 0; q < 4; ++q) vraw[q] = 0;
;         auto pload = [&](int c) {
;             const size_t base = (tok0 + (size_t)c * 16) * 512 + h * 64;
; #pragma unroll
;             for (int t = 0; t < 16; ++t) { const size_t off = base + (size_t)t * 512 + j; kraw[t] = Kb[off]; araw[t] = Ab[off]; rraw[t] = Rb[off]; eraw[t] = EW[off]; }
; #pragma unroll
;             for (int q = 0; q < 4; ++q) vraw[q] = Vb[base + (size_t)(4 * fq + q) * 512 + rg * 16 + fr];
;         };
;         auto pbuild = [&](int c, LAS unsigned char* sl, LAS unsigned char* sc, int cnext) {
;             float W = 1.f;
;             const int m = j >> 5, tp = (j >> 4) & 1, jw = j & 15, pidx = (jw >> 2) * 8 + tp * 4 + (jw & 3);
; #pragma unroll
;             for (int t = 0; t < 16; ++t) {
;                 const float k = bf2f(kraw[t]), a = bf2f(araw[t]), r = bf2f(rraw[t]);
;                 const float q = k * kkc, kp1 = k * (1.f + (a - 1.f) * kac);
;                 *(LAS bf16_t*)(sc + 0 + (t * 64 + j) * 2) = bf1(q * q);
;                 *(LAS bf16_t*)(sc + 2048 + (t * 64 + j) * 2) = bf1(r * kp1 * rkc);
;             }
.Lsc_p_noprio:
	v_cmp_eq_u32_e32 vcc, 0, v1
	v_lshl_add_u32 v4, v2, 2, 0
	s_nop 0
	v_cndmask_b32_e64 v21, 0, 1.0, vcc
	v_cmp_eq_u32_e32 vcc, v4, v1
	s_lshl_b32 s0, s52, 8
	s_nop 0
	v_cndmask_b32_e64 v22, 0, 1.0, vcc
	v_cmp_gt_u32_e32 vcc, v4, v1
	v_readlane_b32 s14, v243, 51
	s_nop 0
	v_cndmask_b32_e64 v30, 0, 1.0, vcc
	v_cmp_ge_u32_e32 vcc, v4, v1
	v_lshl_add_u32 v4, v2, 2, 1
	s_nop 0
	v_cndmask_b32_e64 v34, 0, 1.0, vcc
	v_cmp_eq_u32_e32 vcc, v4, v1
	v_readlane_b32 s15, v243, 52
	s_nop 0
	v_cndmask_b32_e64 v23, 0, 1.0, vcc
	v_cmp_gt_u32_e32 vcc, v4, v1
	s_lshl_b64 s[14:15], s[14:15], 2
	s_nop 0
	v_cndmask_b32_e64 v31, 0, 1.0, vcc
	v_cmp_ge_u32_e32 vcc, v4, v1
	v_lshl_add_u32 v4, v2, 2, 2
	s_nop 0
	v_cndmask_b32_e64 v35, 0, 1.0, vcc
	v_cmp_eq_u32_e32 vcc, v4, v1
	v_readlane_b32 s1, v252, 37
	s_nop 0
	v_cndmask_b32_e64 v28, 0, 1.0, vcc
	v_cmp_gt_u32_e32 vcc, v4, v1
	v_and_b32_e32 v5, 7, v1
	s_nop 0
	v_cndmask_b32_e64 v32, 0, 1.0, vcc
	v_cmp_ge_u32_e32 vcc, v4, v1
	v_lshl_add_u32 v4, v2, 2, 3
	s_nop 0
	v_cndmask_b32_e64 v36, 0, 1.0, vcc
	v_cmp_eq_u32_e32 vcc, v4, v1
	v_lshlrev_b32_e32 v16, 6, v2
	s_nop 0
	v_cndmask_b32_e64 v29, 0, 1.0, vcc
	v_cmp_gt_u32_e32 vcc, v4, v1
	v_mov_b32_e32 v24, 0x3f803f80
	s_nop 0
	v_cndmask_b32_e64 v33, 0, 1.0, vcc
	v_cmp_ge_u32_e32 vcc, v4, v1
	v_lshl_add_u32 v4, v0, 2, s0
	v_readlane_b32 s0, v252, 36
	v_mov_b32_e32 v25, 0x3f803f80
	s_add_u32 s0, s0, s14
	s_addc_u32 s1, s1, s15
	global_load_dword v76, v4, s[0:1]
	v_readlane_b32 s0, v252, 38
	v_readlane_b32 s1, v252, 39
	s_add_u32 s0, s0, s14
	s_addc_u32 s1, s1, s15
	global_load_dword v80, v4, s[0:1]
	v_readlane_b32 s0, v252, 40
	v_readlane_b32 s1, v252, 41
	s_add_u32 s0, s0, s14
	s_addc_u32 s1, s1, s15
	global_load_dword v248, v4, s[0:1]
	s_mul_i32 s0, s54, 4096
	s_lshl_b32 s1, s55, 4
	s_add_u32 s1, s1, s0
	v_add_u32_e32 v8, s1, v1
	s_lshl_b32 s14, s52, 7
	v_lshlrev_b32_e32 v8, 10, v8
	v_lshl_add_u32 v4, v2, 5, s14
	v_lshl_add_u32 v9, v2, 2, s1
	v_add_u32_e32 v8, v8, v4
	s_lshl_b32 s15, s53, 5
	s_add_u32 s14, s14, s15
	v_lshlrev_b32_e32 v9, 10, v9
	v_lshl_add_u32 v4, v1, 1, s14
	s_mul_i32 s0, s55, 2048
	v_add_u32_e32 v9, v9, v4
	v_lshlrev_b32_e32 v4, 1, v2
	s_add_u32 s0, s0, 138240
	v_xor_b32_e32 v4, v4, v5
	v_add_u32_e32 v14, s0, v7
	v_lshlrev_b32_e32 v4, 4, v4
	v_add_u32_e32 v15, s0, v6
	v_lshl_add_u32 v11, v1, 7, v4
	s_mov_b32 s0, 150528
	v_mov_b32_e32 v26, 0x3f803f80
	v_mov_b32_e32 v27, 0x3f803f80
	v_cndmask_b32_e64 v37, 0, 1.0, vcc
	v_lshlrev_b32_e32 v10, 5, v1
	v_xor_b32_e32 v13, 16, v11
	v_add_u32_e32 v16, 10752, v16
	v_lshl_add_u32 v4, v0, 2, s0
	s_mov_b32 s80, 0xbfb8aa3b
	s_mov_b32 s81, 0xbfb8aa3b
	s_waitcnt vmcnt(0)
	ds_write_b32 v4, v76 offset:0
	ds_write_b32 v4, v80 offset:256
	ds_write_b32 v4, v248 offset:512
	global_load_dwordx4 v[40:43], v8, s[26:27]
	global_load_dwordx4 v[44:47], v8, s[26:27] offset:16
	global_load_dwordx4 v[48:51], v8, s[36:37]
	global_load_dwordx4 v[52:55], v8, s[36:37] offset:16
	global_load_dwordx4 v[56:59], v8, s[38:39]
	global_load_dwordx4 v[60:63], v8, s[38:39] offset:16
	global_load_dwordx4 v[64:67], v8, s[46:47]
	global_load_dwordx4 v[68:71], v8, s[46:47] offset:16
	global_load_ushort v72, v9, s[60:61] offset:0
	global_load_ushort v73, v9, s[60:61] offset:1024
	v_lshl_add_u32 v38, v2, 6, s0
	global_load_ushort v74, v9, s[60:61] offset:2048
	global_load_ushort v75, v9, s[60:61] offset:3072
	s_lshl_b32 s0, s1, 5
	global_load_ushort v84, v9, s[60:61] offset:32
	s_lshl_b32 s14, s52, 2
	global_load_ushort v85, v9, s[60:61] offset:1056
	s_add_u32 s0, s0, s14
	global_load_ushort v86, v9, s[60:61] offset:2080
	s_add_u32 s0, s0, 0x9000000
	global_load_ushort v87, v9, s[60:61] offset:3104
	s_add_u32 s50, s74, s0
	v_add_u32_e32 v8, 0x18000, v8
	v_add_u32_e32 v9, 0x18000, v9
	s_mul_i32 s57, s55, 11520
	s_mov_b32 s56, 0
	s_addc_u32 s51, s75, 0
	s_mov_b32 s58, s55
	s_mov_b32 s42, 0
.Lsc_p_loop:
	s_cmp_ge_u32 s58, 256
	s_cbranch_scc1 .Lsc_p_skip
	s_add_u32 s0, s57, s56
	v_add_u32_e32 v17, s0, v11
	v_add_u32_e32 v18, s0, v13
	v_add_u32_e32 v19, s0, v6
	v_add_u32_e32 v20, s0, v16
	s_waitcnt vmcnt(0)
	v_lshl_or_b32 v76, v73, 16, v72
	v_lshl_or_b32 v77, v75, 16, v74
	v_lshl_or_b32 v80, v85, 16, v84
	v_lshl_or_b32 v81, v87, 16, v86
	v_and_b32_e32 v89, 0xffff0000, v40
	v_lshlrev_b32_e32 v88, 16, v40
	v_and_b32_e32 v105, 0xffff0000, v48
	v_lshlrev_b32_e32 v104, 16, v48
	v_and_b32_e32 v121, 0xffff0000, v56
	v_lshlrev_b32_e32 v120, 16, v56
	v_cvt_f32_f16_sdwa v153, v64 dst_sel:DWORD dst_unused:UNUSED_PAD src0_sel:WORD_1
	v_cvt_f32_f16_e32 v152, v64
	v_and_b32_e32 v91, 0xffff0000, v41
	v_lshlrev_b32_e32 v90, 16, v41
	v_and_b32_e32 v107, 0xffff0000, v49
	v_lshlrev_b32_e32 v106, 16, v49
	v_and_b32_e32 v123, 0xffff0000, v57
	v_lshlrev_b32_e32 v122, 16, v57
	v_cvt_f32_f16_sdwa v155, v65 dst_sel:DWORD dst_unused:UNUSED_PAD src0_sel:WORD_1
	v_cvt_f32_f16_e32 v154, v65
	v_and_b32_e32 v93, 0xffff0000, v42
	v_lshlrev_b32_e32 v92, 16, v42
	v_and_b32_e32 v109, 0xffff0000, v50
	v_lshlrev_b32_e32 v108, 16, v50
	v_and_b32_e32 v125, 0xffff0000, v58
	v_lshlrev_b32_e32 v124, 16, v58
	v_cvt_f32_f16_sdwa v157, v66 dst_sel:DWORD dst_unused:UNUSED_PAD src0_sel:WORD_1
	v_cvt_f32_f16_e32 v156, v66
	v_and_b32_e32 v95, 0xffff0000, v43
	v_lshlrev_b32_e32 v94, 16, v43
	v_and_b32_e32 v111, 0xffff0000, v51
	v_lshlrev_b32_e32 v110, 16, v51
	v_and_b32_e32 v127, 0xffff0000, v59
	v_lshlrev_b32_e32 v126, 16, v59
	v_cvt_f32_f16_sdwa v159, v67 dst_sel:DWORD dst_unused:UNUSED_PAD src0_sel:WORD_1
	v_cvt_f32_f16_e32 v158, v67
	v_and_b32_e32 v97, 0xffff0000, v44
	v_lshlrev_b32_e32 v96, 16, v44
	v_and_b32_e32 v113, 0xffff0000, v52
	v_lshlrev_b32_e32 v112, 16, v52
	v_and_b32_e32 v129, 0xffff0000, v60
	v_lshlrev_b32_e32 v128, 16, v60
	v_cvt_f32_f16_sdwa v161, v68 dst_sel:DWORD dst_unused:UNUSED_PAD src0_sel:WORD_1
	v_cvt_f32_f16_e32 v160, v68
	v_and_b32_e32 v99, 0xffff0000, v45
	v_lshlrev_b32_e32 v98, 16, v45
	v_and_b32_e32 v115, 0xffff0000, v53
	v_lshlrev_b32_e32 v114, 16, v53
	v_and_b32_e32 v131, 0xffff0000, v61
	v_lshlrev_b32_e32 v130, 16, v61
	v_cvt_f32_f16_sdwa v163, v69 dst_sel:DWORD dst_unused:UNUSED_PAD src0_sel:WORD_1
	v_cvt_f32_f16_e32 v162, v69
	v_and_b32_e32 v101, 0xffff0000, v46
	v_lshlrev_b32_e32 v100, 16, v46
	v_and_b32_e32 v117, 0xffff0000, v54
	v_lshlrev_b32_e32 v116, 16, v54
	v_and_b32_e32 v133, 0xffff0000, v62
	v_lshlrev_b32_e32 v132, 16, v62
	v_cvt_f32_f16_sdwa v165, v70 dst_sel:DWORD dst_unused:UNUSED_PAD src0_sel:WORD_1
	v_cvt_f32_f16_e32 v164, v70
	v_and_b32_e32 v103, 0xffff0000, v47
	v_lshlrev_b32_e32 v102, 16, v47
	v_and_b32_e32 v119, 0xffff0000, v55
	v_lshlrev_b32_e32 v118, 16, v55
	v_and_b32_e32 v135, 0xffff0000, v63
	v_lshlrev_b32_e32 v134, 16, v63
	v_cvt_f32_f16_sdwa v167, v71 dst_sel:DWORD dst_unused:UNUSED_PAD src0_sel:WORD_1
	v_cvt_f32_f16_e32 v166, v71
	ds_write_b64 v19, v[76:77] offset:10240
	s_add_u32 s0, s58, 6
	ds_write_b64 v19, v[80:81] offset:11008
	s_cmp_ge_u32 s0, 256
	s_cbranch_scc1 .Lsc_p_nopf
; __device__ __forceinline__ void phase_scan2(const Params& p, int l, LAS unsigned char* lds) {
;     ...
;             for (int t = 0; t < 16; ++t) { const size_t off = base + (size_t)t * 512 + j; kraw[t] = Kb[off]; araw[t] = Ab[off]; rraw[t] = Rb[off]; eraw[t] = EW[off]; }
; #pragma unroll
;             for (int q = 0; q < 4; ++q) vraw[q] = Vb[base + (size_t)(4 * fq + q) * 512 + rg * 16 + fr];
;         };
;         auto pbuild = [&](int c, LAS unsigned char* sl, LAS unsigned char* sc, int cnext) {
;             float W = 1.f;
;             const int m = j >> 5, tp = (j >> 4) & 1, jw = j & 15, pidx = (jw >> 2) * 8 + tp * 4 + (jw & 3);
; #pragma unroll
;             for (int t = 0; t < 16; ++t) {
;                 const float k = bf2f(kraw[t]), a = bf2f(araw[t]), r = bf2f(rraw[t]);
;                 const float q = k * kkc, kp1 = k * (1.f + (a - 1.f) * kac);
;                 *(LAS bf16_t*)(sc + 0 + (t * 64 + j) * 2) = bf1(q * q);
;                 *(LAS bf16_t*)(sc + 2048 + (t * 64 + j) * 2) = bf1(r * kp1 * rkc);
;             }
;             asm volatile("s_waitcnt lgkmcnt(0)" ::: "memory");
;             { const bf16x8 ones = __builtin_bit_cast(bf16x8, (u32x4){0x3F803F80u, 0x3F803F80u, 0x3F803F80u, 0x3F803F80u});
;               f32x4 sq = (f32x4){0.f, 0.f, 0.f, 0.f}, sb = sq;
; #pragma unroll
;               for (int kk2 = 0; kk2 < 2; ++kk2) {
;                   const bf16x8 fa = *(LAS const bf16x8*)(sc + 0 + (fr * 64 + kk2 * 32 + fq * 8) * 2), fu = *(LAS const bf16x8*)(sc + 2048 + (fr * 64 + kk2 * 32 + fq * 8) * 2);
;                   sq = __builtin_amdgcn_mfma_f32_16x16x32_bf16(fa, ones, sq, 0, 0, 0); sb = __builtin_amdgcn_mfma_f32_16x16x32_bf16(fu, ones, sb, 0, 0, 0);
;               }
;               if (fr == 0) { *(LAS f32x4*)(sl + SC_X + fq * 16) = sq; *(LAS f32x4*)(sl + SC_X + 64 + fq * 16) = sb; }
;               asm volatile("s_waitcnt lgkmcnt(0)" ::: "memory");
;               if (rg == 0 && lane < 16) CB[(tok0 + (size_t)c * 16 + lane) * 8 + h] = *(LAS const float*)(sl + SC_X + 64 + lane * 4);
;               asm volatile("s_waitcnt lgkmcnt(0)" ::: "memory");
;             }
; #pragma unroll
;             for (int t = 0; t < 16; ++t) {
;                 const float k = bf2f(kraw[t]), a = bf2f(araw[t]), r = bf2f(rraw[t]), ew = (float)eraw[t];
;                 const float kk = k * kkc * rsqrtf(fmaxf(*(LAS const float*)(sl + SC_X + t * 4), 1e-24f));
	global_load_dwordx4 v[40:43], v8, s[26:27]
	global_load_dwordx4 v[44:47], v8, s[26:27] offset:16
	global_load_dwordx4 v[48:51], v8, s[36:37]
	global_load_dwordx4 v[52:55], v8, s[36:37] offset:16
	global_load_dwordx4 v[56:59], v8, s[38:39]
	global_load_dwordx4 v[60:63], v8, s[38:39] offset:16
	global_load_dwordx4 v[64:67], v8, s[46:47]
	global_load_dwordx4 v[68:71], v8, s[46:47] offset:16
	global_load_ushort v72, v9, s[60:61] offset:0
	global_load_ushort v73, v9, s[60:61] offset:1024
	global_load_ushort v74, v9, s[60:61] offset:2048
	global_load_ushort v75, v9, s[60:61] offset:3072
	global_load_ushort v84, v9, s[60:61] offset:32
	global_load_ushort v85, v9, s[60:61] offset:1056
	global_load_ushort v86, v9, s[60:61] offset:2080
	global_load_ushort v87, v9, s[60:61] offset:3104
	v_add_u32_e32 v8, 0x18000, v8
	v_add_u32_e32 v9, 0x18000, v9
	s_nop 1
.Lsc_p_nopf:
	ds_read_b128 v[220:223], v38 offset:256
	ds_read_b128 v[224:227], v38 offset:272
	ds_read_b128 v[228:231], v38 offset:0
	ds_read_b128 v[232:235], v38 offset:16
	ds_read_b128 v[236:239], v38 offset:512
	ds_read_b128 v[244:247], v38 offset:528
	s_waitcnt lgkmcnt(0)
	v_add_f32_e32 v76, -1.0, v104
	v_add_f32_e32 v77, -1.0, v105
	v_add_f32_e32 v186, -1.0, v106
	v_add_f32_e32 v187, -1.0, v107
	v_pk_fma_f32 v[76:77], v[220:221], v[76:77], 1.0 op_sel_hi:[1,1,0]
	v_pk_fma_f32 v[186:187], v[222:223], v[186:187], 1.0 op_sel_hi:[1,1,0]
	v_pk_mul_f32 v[136:137], v[76:77], v[88:89]
	v_pk_mul_f32 v[138:139], v[186:187], v[90:91]
	v_pk_mul_f32 v[248:249], v[136:137], v[120:121]
	v_pk_mul_f32 v[194:195], v[138:139], v[122:123]
	v_add_f32_e32 v76, -1.0, v108
	v_add_f32_e32 v77, -1.0, v109
	v_add_f32_e32 v186, -1.0, v110
	v_add_f32_e32 v187, -1.0, v111
	v_pk_mul_f32 v[88:89], v[228:229], v[88:89]
	v_pk_mul_f32 v[248:249], v[236:237], v[248:249]
	v_pk_mul_f32 v[90:91], v[230:231], v[90:91]
	v_pk_mul_f32 v[194:195], v[238:239], v[194:195]
	v_pk_fma_f32 v[76:77], v[224:225], v[76:77], 1.0 op_sel_hi:[1,1,0]
	v_pk_fma_f32 v[186:187], v[226:227], v[186:187], 1.0 op_sel_hi:[1,1,0]
	v_pk_mul_f32 v[80:81], v[88:89], v[88:89]
	v_cvt_pk_bf16_f32 v204, v248, v249
	v_pk_mul_f32 v[188:189], v[90:91], v[90:91]
	v_cvt_pk_bf16_f32 v205, v194, v195
	v_pk_mul_f32 v[140:141], v[76:77], v[92:93]
	v_pk_mul_f32 v[142:143], v[186:187], v[94:95]
	v_cvt_pk_bf16_f32 v196, v80, v81
	v_cvt_pk_bf16_f32 v197, v188, v189
	v_pk_mul_f32 v[92:93], v[232:233], v[92:93]
	v_pk_mul_f32 v[248:249], v[140:141], v[124:125]
	v_pk_mul_f32 v[94:95], v[234:235], v[94:95]
	v_pk_mul_f32 v[194:195], v[142:143], v[126:127]
	ds_read_b128 v[220:223], v38 offset:288
	ds_read_b128 v[224:227], v38 offset:304
	v_pk_mul_f32 v[80:81], v[92:93], v[92:93]
	v_pk_mul_f32 v[248:249], v[244:245], v[248:249]
	v_pk_mul_f32 v[188:189], v[94:95], v[94:95]
	v_pk_mul_f32 v[194:195], v[246:247], v[194:195]
	ds_read_b128 v[228:231], v38 offset:32
	ds_read_b128 v[232:235], v38 offset:48
	v_cvt_pk_bf16_f32 v198, v80, v81
	v_cvt_pk_bf16_f32 v206, v248, v249
	v_cvt_pk_bf16_f32 v199, v188, v189
	v_cvt_pk_bf16_f32 v207, v194, v195
	ds_read_b128 v[236:239], v38 offset:544
	ds_read_b128 v[244:247], v38 offset:560
	s_waitcnt lgkmcnt(0)
	v_add_f32_e32 v76, -1.0, v112
	v_add_f32_e32 v77, -1.0, v113
	v_add_f32_e32 v186, -1.0, v114
	v_add_f32_e32 v187, -1.0, v115
	v_pk_fma_f32 v[76:77], v[220:221], v[76:77], 1.0 op_sel_hi:[1,1,0]
	v_pk_fma_f32 v[186:187], v[222:223], v[186:187], 1.0 op_sel_hi:[1,1,0]
	v_pk_mul_f32 v[144:145], v[76:77], v[96:97]
	v_pk_mul_f32 v[146:147], v[186:187], v[98:99]
	v_pk_mul_f32 v[248:249], v[144:145], v[128:129]
	v_pk_mul_f32 v[194:195], v[146:147], v[130:131]
	v_add_f32_e32 v76, -1.0, v116
	v_add_f32_e32 v77, -1.0, v117
	v_add_f32_e32 v186, -1.0, v118
	v_add_f32_e32 v187, -1.0, v119
	v_pk_mul_f32 v[96:97], v[228:229], v[96:97]
	v_pk_mul_f32 v[248:249], v[236:237], v[248:249]
	v_pk_mul_f32 v[98:99], v[230:231], v[98:99]
	v_pk_mul_f32 v[194:195], v[238:239], v[194:195]
	v_pk_fma_f32 v[76:77], v[224:225], v[76:77], 1.0 op_sel_hi:[1,1,0]
	v_pk_fma_f32 v[186:187], v[226:227], v[186:187], 1.0 op_sel_hi:[1,1,0]
	v_mfma_f32_16x16x32_bf16 v[168:171], v[24:27], v[196:199], 0
	v_mfma_f32_16x16x32_bf16 v[172:175], v[24:27], v[204:207], 0
	v_pk_mul_f32 v[80:81], v[96:97], v[96:97]
	v_cvt_pk_bf16_f32 v208, v248, v249
	v_pk_mul_f32 v[188:189], v[98:99], v[98:99]
	v_cvt_pk_bf16_f32 v209, v194, v195
	v_pk_mul_f32 v[148:149], v[76:77], v[100:101]
	v_pk_mul_f32 v[150:151], v[186:187], v[102:103]
	v_cvt_pk_bf16_f32 v200, v80, v81
	v_cvt_pk_bf16_f32 v201, v188, v189
	v_pk_mul_f32 v[100:101], v[232:233], v[100:101]
	v_pk_mul_f32 v[248:249], v[148:149], v[132:133]
	v_pk_mul_f32 v[102:103], v[234:235], v[102:103]
	v_pk_mul_f32 v[194:195], v[150:151], v[134:135]
	v_pk_mul_f32 v[80:81], v[100:101], v[100:101]
	v_pk_mul_f32 v[248:249], v[244:245], v[248:249]
	v_pk_mul_f32 v[188:189], v[102:103], v[102:103]
	v_pk_mul_f32 v[194:195], v[246:247], v[194:195]
	v_cvt_pk_bf16_f32 v202, v80, v81
	v_cvt_pk_bf16_f32 v210, v248, v249
	v_cvt_pk_bf16_f32 v203, v188, v189
	v_cvt_pk_bf16_f32 v211, v194, v195
	v_pk_mul_f32 v[152:153], v[152:153], s[80:81]
	v_pk_mul_f32 v[154:155], v[154:155], s[80:81]
	v_pk_mul_f32 v[156:157], v[156:157], s[80:81]
	v_pk_mul_f32 v[158:159], v[158:159], s[80:81]
	v_pk_mul_f32 v[160:161], v[160:161], s[80:81]
	v_pk_mul_f32 v[162:163], v[162:163], s[80:81]
	v_pk_mul_f32 v[164:165], v[164:165], s[80:81]
	v_pk_mul_f32 v[166:167], v[166:167], s[80:81]
	v_mfma_f32_16x16x32_bf16 v[168:171], v[24:27], v[200:203], v[168:171]
	v_mfma_f32_16x16x32_bf16 v[172:175], v[24:27], v[208:211], v[172:175]
	v_add_f32_dpp v152, v152, v152 row_shr:1 row_mask:0xf bank_mask:0xf bound_ctrl:1
; #define LAS __attribute__((address_space(3)))
; __device__ __forceinline__ float bf2f(bf16_t b) { return __uint_as_float(((unsigned)b) << 16); }
; __device__ __forceinline__ void phase_scan2(const Params& p, int l, LAS unsigned char* lds) {
;     ...
;               if (rg == 0 && lane < 16) CB[(tok0 + (size_t)c * 16 + lane) * 8 + h] = *(LAS const float*)(sl + SC_X + 64 + lane * 4);
;               asm volatile("s_waitcnt lgkmcnt(0)" ::: "memory");
;             }
; #pragma unroll
;             for (int t = 0; t < 16; ++t) {
;                 const float k = bf2f(kraw[t]), a = bf2f(araw[t]), r = bf2f(rraw[t]), ew = (float)eraw[t];
;                 const float kk = k * kkc * rsqrtf(fmaxf(*(LAS const float*)(sl + SC_X + t * 4), 1e-24f));
;                 const float kp = k * (1.f + (a - 1.f) * kac);
;                 const float at = -kk * W;
;                 W *= __expf(-ew);
;                 const float rt = r * W, iw = __builtin_amdgcn_rcpf(W);
	v_add_f32_dpp v153, v153, v153 row_shr:1 row_mask:0xf bank_mask:0xf bound_ctrl:1
	v_add_f32_dpp v154, v154, v154 row_shr:1 row_mask:0xf bank_mask:0xf bound_ctrl:1
	v_add_f32_dpp v155, v155, v155 row_shr:1 row_mask:0xf bank_mask:0xf bound_ctrl:1
	v_add_f32_dpp v156, v156, v156 row_shr:1 row_mask:0xf bank_mask:0xf bound_ctrl:1
	v_add_f32_dpp v157, v157, v157 row_shr:1 row_mask:0xf bank_mask:0xf bound_ctrl:1
	v_add_f32_dpp v158, v158, v158 row_shr:1 row_mask:0xf bank_mask:0xf bound_ctrl:1
	v_add_f32_dpp v159, v159, v159 row_shr:1 row_mask:0xf bank_mask:0xf bound_ctrl:1
	v_add_f32_dpp v160, v160, v160 row_shr:1 row_mask:0xf bank_mask:0xf bound_ctrl:1
	v_add_f32_dpp v161, v161, v161 row_shr:1 row_mask:0xf bank_mask:0xf bound_ctrl:1
	v_add_f32_dpp v162, v162, v162 row_shr:1 row_mask:0xf bank_mask:0xf bound_ctrl:1
	v_add_f32_dpp v163, v163, v163 row_shr:1 row_mask:0xf bank_mask:0xf bound_ctrl:1
	v_add_f32_dpp v164, v164, v164 row_shr:1 row_mask:0xf bank_mask:0xf bound_ctrl:1
	v_add_f32_dpp v165, v165, v165 row_shr:1 row_mask:0xf bank_mask:0xf bound_ctrl:1
	v_add_f32_dpp v166, v166, v166 row_shr:1 row_mask:0xf bank_mask:0xf bound_ctrl:1
	v_add_f32_dpp v167, v167, v167 row_shr:1 row_mask:0xf bank_mask:0xf bound_ctrl:1
	v_add_f32_dpp v152, v152, v152 row_shr:2 row_mask:0xf bank_mask:0xf bound_ctrl:1
	v_add_f32_dpp v153, v153, v153 row_shr:2 row_mask:0xf bank_mask:0xf bound_ctrl:1
	v_add_f32_dpp v154, v154, v154 row_shr:2 row_mask:0xf bank_mask:0xf bound_ctrl:1
	v_add_f32_dpp v155, v155, v155 row_shr:2 row_mask:0xf bank_mask:0xf bound_ctrl:1
	v_add_f32_dpp v156, v156, v156 row_shr:2 row_mask:0xf bank_mask:0xf bound_ctrl:1
	v_add_f32_dpp v157, v157, v157 row_shr:2 row_mask:0xf bank_mask:0xf bound_ctrl:1
	v_add_f32_dpp v158, v158, v158 row_shr:2 row_mask:0xf bank_mask:0xf bound_ctrl:1
	v_add_f32_dpp v159, v159, v159 row_shr:2 row_mask:0xf bank_mask:0xf bound_ctrl:1
	v_add_f32_dpp v160, v160, v160 row_shr:2 row_mask:0xf bank_mask:0xf bound_ctrl:1
	v_add_f32_dpp v161, v161, v161 row_shr:2 row_mask:0xf bank_mask:0xf bound_ctrl:1
	v_add_f32_dpp v162, v162, v162 row_shr:2 row_mask:0xf bank_mask:0xf bound_ctrl:1
	v_add_f32_dpp v163, v163, v163 row_shr:2 row_mask:0xf bank_mask:0xf bound_ctrl:1
	v_add_f32_dpp v164, v164, v164 row_shr:2 row_mask:0xf bank_mask:0xf bound_ctrl:1
	v_add_f32_dpp v165, v165, v165 row_shr:2 row_mask:0xf bank_mask:0xf bound_ctrl:1
	v_add_f32_dpp v166, v166, v166 row_shr:2 row_mask:0xf bank_mask:0xf bound_ctrl:1
	v_add_f32_dpp v167, v167, v167 row_shr:2 row_mask:0xf bank_mask:0xf bound_ctrl:1
	v_add_f32_dpp v152, v152, v152 row_shr:4 row_mask:0xf bank_mask:0xf bound_ctrl:1
	v_add_f32_dpp v153, v153, v153 row_shr:4 row_mask:0xf bank_mask:0xf bound_ctrl:1
	v_add_f32_dpp v154, v154, v154 row_shr:4 row_mask:0xf bank_mask:0xf bound_ctrl:1
	v_add_f32_dpp v155, v155, v155 row_shr:4 row_mask:0xf bank_mask:0xf bound_ctrl:1
	v_add_f32_dpp v156, v156, v156 row_shr:4 row_mask:0xf bank_mask:0xf bound_ctrl:1
	v_add_f32_dpp v157, v157, v157 row_shr:4 row_mask:0xf bank_mask:0xf bound_ctrl:1
	v_add_f32_dpp v158, v158, v158 row_shr:4 row_mask:0xf bank_mask:0xf bound_ctrl:1
	v_add_f32_dpp v159, v159, v159 row_shr:4 row_mask:0xf bank_mask:0xf bound_ctrl:1
	v_add_f32_dpp v160, v160, v160 row_shr:4 row_mask:0xf bank_mask:0xf bound_ctrl:1
	v_add_f32_dpp v161, v161, v161 row_shr:4 row_mask:0xf bank_mask:0xf bound_ctrl:1
	v_add_f32_dpp v162, v162, v162 row_shr:4 row_mask:0xf bank_mask:0xf bound_ctrl:1
	v_add_f32_dpp v163, v163, v163 row_shr:4 row_mask:0xf bank_mask:0xf bound_ctrl:1
	v_add_f32_dpp v164, v164, v164 row_shr:4 row_mask:0xf bank_mask:0xf bound_ctrl:1
	v_add_f32_dpp v165, v165, v165 row_shr:4 row_mask:0xf bank_mask:0xf bound_ctrl:1
	v_add_f32_dpp v166, v166, v166 row_shr:4 row_mask:0xf bank_mask:0xf bound_ctrl:1
	v_add_f32_dpp v167, v167, v167 row_shr:4 row_mask:0xf bank_mask:0xf bound_ctrl:1
	v_add_f32_dpp v152, v152, v152 row_shr:8 row_mask:0xf bank_mask:0xf bound_ctrl:1
	v_add_f32_dpp v153, v153, v153 row_shr:8 row_mask:0xf bank_mask:0xf bound_ctrl:1
	v_add_f32_dpp v154, v154, v154 row_shr:8 row_mask:0xf bank_mask:0xf bound_ctrl:1
	v_add_f32_dpp v155, v155, v155 row_shr:8 row_mask:0xf bank_mask:0xf bound_ctrl:1
	v_add_f32_dpp v156, v156, v156 row_shr:8 row_mask:0xf bank_mask:0xf bound_ctrl:1
	v_add_f32_dpp v157, v157, v157 row_shr:8 row_mask:0xf bank_mask:0xf bound_ctrl:1
	v_add_f32_dpp v158, v158, v158 row_shr:8 row_mask:0xf bank_mask:0xf bound_ctrl:1
	v_add_f32_dpp v159, v159, v159 row_shr:8 row_mask:0xf bank_mask:0xf bound_ctrl:1
	v_add_f32_dpp v160, v160, v160 row_shr:8 row_mask:0xf bank_mask:0xf bound_ctrl:1
	v_add_f32_dpp v161, v161, v161 row_shr:8 row_mask:0xf bank_mask:0xf bound_ctrl:1
	v_add_f32_dpp v162, v162, v162 row_shr:8 row_mask:0xf bank_mask:0xf bound_ctrl:1
	v_add_f32_dpp v163, v163, v163 row_shr:8 row_mask:0xf bank_mask:0xf bound_ctrl:1
	v_add_f32_dpp v164, v164, v164 row_shr:8 row_mask:0xf bank_mask:0xf bound_ctrl:1
	v_add_f32_dpp v165, v165, v165 row_shr:8 row_mask:0xf bank_mask:0xf bound_ctrl:1
	v_add_f32_dpp v166, v166, v166 row_shr:8 row_mask:0xf bank_mask:0xf bound_ctrl:1
	v_add_f32_dpp v167, v167, v167 row_shr:8 row_mask:0xf bank_mask:0xf bound_ctrl:1
	v_exp_f32_e32 v196, v152
	v_exp_f32_e32 v197, v153
	v_exp_f32_e32 v198, v154
	v_exp_f32_e32 v199, v155
	v_exp_f32_e32 v200, v156
	v_exp_f32_e32 v201, v157
	v_exp_f32_e32 v202, v158
	v_exp_f32_e32 v203, v159
	v_exp_f32_e32 v204, v160
	v_exp_f32_e32 v205, v161
	v_exp_f32_e32 v206, v162
	v_exp_f32_e32 v207, v163
	v_exp_f32_e32 v208, v164
	v_exp_f32_e32 v209, v165
	v_exp_f32_e32 v210, v166
	v_exp_f32_e32 v211, v167
	v_max_f32_e32 v176, 0x179abe15, v168
	v_exp_f32_e64 v152, -v152
	v_rsq_f32_e32 v176, v176
	v_exp_f32_e64 v153, -v153
	v_exp_f32_e64 v154, -v154
	v_exp_f32_e64 v155, -v155
	v_exp_f32_e64 v156, -v156
	v_exp_f32_e64 v157, -v157
	v_exp_f32_e64 v158, -v158
	v_exp_f32_e64 v159, -v159
	v_exp_f32_e64 v160, -v160
	v_exp_f32_e64 v161, -v161
	v_exp_f32_e64 v162, -v162
	v_exp_f32_e64 v163, -v163
	v_exp_f32_e64 v164, -v164
	v_exp_f32_e64 v165, -v165
	v_exp_f32_e64 v166, -v166
	v_exp_f32_e64 v167, -v167
	s_cmp_lg_u32 s53, 0
	s_nop 0
	s_cbranch_scc1 .Lsc_p_nocb
	s_mov_b64 exec, 0xffff
	global_store_dword v10, v172, s[50:51]
	s_mov_b64 exec, -1
; #define LAS __attribute__((address_space(3)))
; __device__ __forceinline__ unsigned pk_bf16(float lo, float hi) { const f32x2_t f = {lo, hi}; return __builtin_bit_cast(unsigned, __builtin_convertvector(f, bf16x2_t)); }
; __device__ __forceinline__ float bf2f(bf16_t b) { return __uint_as_float(((unsigned)b) << 16); }
; __device__ __forceinline__ void phase_scan2(const Params& p, int l, LAS unsigned char* lds) {
;     ...
; #pragma unroll
;             for (int t = 0; t < 16; ++t) {
;                 const float k = bf2f(kraw[t]), a = bf2f(araw[t]), r = bf2f(rraw[t]), ew = (float)eraw[t];
;                 const float kk = k * kkc * rsqrtf(fmaxf(*(LAS const float*)(sl + SC_X + t * 4), 1e-24f));
;                 const float kp = k * (1.f + (a - 1.f) * kac);
;                 const float at = -kk * W;
;                 W *= __expf(-ew);
;                 const float rt = r * W, iw = __builtin_amdgcn_rcpf(W);
;                 const unsigned wbk = pk_bf16(kk * a * iw, kp * iw), war = pk_bf16(at, rt);
;                 const bf16_t bh = (bf16_t)(wbk & 0xffffu), kh = (bf16_t)(wbk >> 16), ah = (bf16_t)(war & 0xffffu), rh = (bf16_t)(war >> 16);
;                 *(LAS bf16_t*)(sl + SC_AT + ((m * 16 + t) * 32 + pidx) * 2) = ah;
;                 *(LAS bf16_t*)(sl + SC_RT + ((m * 16 + t) * 32 + pidx) * 2) = rh;
;                 *(LAS bf16_t*)(sl + SC_BBT + (j * SC_BS + t) * 2) = bh;
;                 *(LAS bf16_t*)(sl + SC_KBT + (j * SC_BS + t) * 2) = kh;
;                 *(LAS bf16_t*)(sc + 0 + ((m * 16 + t) * 32 + pidx) * 2) = bh;
;                 *(LAS bf16_t*)(sc + 2048 + ((m * 16 + t) * 32 + pidx) * 2) = kh;
;             }
.Lsc_p_nocb:
	v_mov_b32_dpp v76, v196 row_shr:1 row_mask:0xf bank_mask:0xf bound_ctrl:1
	v_mov_b32_dpp v77, v197 row_shr:1 row_mask:0xf bank_mask:0xf bound_ctrl:1
	v_mov_b32_dpp v186, v198 row_shr:1 row_mask:0xf bank_mask:0xf bound_ctrl:1
	v_mov_b32_dpp v187, v199 row_shr:1 row_mask:0xf bank_mask:0xf bound_ctrl:1
	v_pk_mul_f32 v[88:89], v[88:89], v[176:177] op_sel_hi:[1,0]
	v_max_f32_e32 v76, v76, v21
	v_max_f32_e32 v77, v77, v21
	v_pk_mul_f32 v[90:91], v[90:91], v[176:177] op_sel_hi:[1,0]
	v_max_f32_e32 v186, v186, v21
	v_max_f32_e32 v187, v187, v21
	v_pk_mul_f32 v[76:77], v[88:89], v[76:77] neg_lo:[1,0] neg_hi:[1,0]
	v_pk_mul_f32 v[186:187], v[90:91], v[186:187] neg_lo:[1,0] neg_hi:[1,0]
	v_cvt_pk_bf16_f32 v168, v76, v77
	v_cvt_pk_bf16_f32 v169, v186, v187
	v_mov_b32_dpp v76, v200 row_shr:1 row_mask:0xf bank_mask:0xf bound_ctrl:1
	v_mov_b32_dpp v77, v201 row_shr:1 row_mask:0xf bank_mask:0xf bound_ctrl:1
	v_mov_b32_dpp v186, v202 row_shr:1 row_mask:0xf bank_mask:0xf bound_ctrl:1
	v_mov_b32_dpp v187, v203 row_shr:1 row_mask:0xf bank_mask:0xf bound_ctrl:1
	v_pk_mul_f32 v[92:93], v[92:93], v[176:177] op_sel_hi:[1,0]
	v_max_f32_e32 v76, v76, v21
	v_max_f32_e32 v77, v77, v21
	v_pk_mul_f32 v[94:95], v[94:95], v[176:177] op_sel_hi:[1,0]
	v_max_f32_e32 v186, v186, v21
	v_max_f32_e32 v187, v187, v21
	v_pk_mul_f32 v[76:77], v[92:93], v[76:77] neg_lo:[1,0] neg_hi:[1,0]
	v_pk_mul_f32 v[186:187], v[94:95], v[186:187] neg_lo:[1,0] neg_hi:[1,0]
	v_cvt_pk_bf16_f32 v170, v76, v77
	v_cvt_pk_bf16_f32 v171, v186, v187
	v_mov_b32_dpp v76, v204 row_shr:1 row_mask:0xf bank_mask:0xf bound_ctrl:1
	v_mov_b32_dpp v77, v205 row_shr:1 row_mask:0xf bank_mask:0xf bound_ctrl:1
	v_mov_b32_dpp v186, v206 row_shr:1 row_mask:0xf bank_mask:0xf bound_ctrl:1
	v_mov_b32_dpp v187, v207 row_shr:1 row_mask:0xf bank_mask:0xf bound_ctrl:1
	v_pk_mul_f32 v[80:81], v[120:121], v[196:197]
	v_pk_mul_f32 v[104:105], v[88:89], v[104:105]
	v_pk_mul_f32 v[188:189], v[122:123], v[198:199]
	v_pk_mul_f32 v[106:107], v[90:91], v[106:107]
	v_pk_mul_f32 v[96:97], v[96:97], v[176:177] op_sel_hi:[1,0]
	v_max_f32_e32 v76, v76, v21
	v_max_f32_e32 v77, v77, v21
	v_pk_mul_f32 v[98:99], v[98:99], v[176:177] op_sel_hi:[1,0]
	v_max_f32_e32 v186, v186, v21
	v_max_f32_e32 v187, v187, v21
	v_pk_mul_f32 v[248:249], v[104:105], v[152:153]
	v_cvt_pk_bf16_f32 v220, v80, v81
	v_pk_mul_f32 v[194:195], v[106:107], v[154:155]
	v_cvt_pk_bf16_f32 v221, v188, v189
	v_pk_mul_f32 v[76:77], v[96:97], v[76:77] neg_lo:[1,0] neg_hi:[1,0]
	v_pk_mul_f32 v[186:187], v[98:99], v[186:187] neg_lo:[1,0] neg_hi:[1,0]
	v_pk_mul_f32 v[250:251], v[136:137], v[152:153]
	v_cvt_pk_bf16_f32 v228, v248, v249
	v_pk_mul_f32 v[212:213], v[138:139], v[154:155]
	v_cvt_pk_bf16_f32 v229, v194, v195
	v_pk_mul_f32 v[80:81], v[124:125], v[200:201]
	v_pk_mul_f32 v[108:109], v[92:93], v[108:109]
	v_pk_mul_f32 v[188:189], v[126:127], v[202:203]
	v_pk_mul_f32 v[110:111], v[94:95], v[110:111]
	v_cvt_pk_bf16_f32 v172, v76, v77
	v_cvt_pk_bf16_f32 v173, v186, v187
	v_cvt_pk_bf16_f32 v236, v250, v251
	v_cvt_pk_bf16_f32 v237, v212, v213
	v_pk_mul_f32 v[248:249], v[108:109], v[156:157]
	v_cvt_pk_bf16_f32 v222, v80, v81
	v_pk_mul_f32 v[194:195], v[110:111], v[158:159]
	v_cvt_pk_bf16_f32 v223, v188, v189
	v_mov_b32_dpp v76, v208 row_shr:1 row_mask:0xf bank_mask:0xf bound_ctrl:1
	v_mov_b32_dpp v77, v209 row_shr:1 row_mask:0xf bank_mask:0xf bound_ctrl:1
	v_mov_b32_dpp v186, v210 row_shr:1 row_mask:0xf bank_mask:0xf bound_ctrl:1
	v_mov_b32_dpp v187, v211 row_shr:1 row_mask:0xf bank_mask:0xf bound_ctrl:1
	v_pk_mul_f32 v[250:251], v[140:141], v[156:157]
	v_cvt_pk_bf16_f32 v230, v248, v249
	v_pk_mul_f32 v[212:213], v[142:143], v[158:159]
	v_cvt_pk_bf16_f32 v231, v194, v195
	v_pk_mul_f32 v[80:81], v[128:129], v[204:205]
	v_pk_mul_f32 v[112:113], v[96:97], v[112:113]
	v_pk_mul_f32 v[188:189], v[130:131], v[206:207]
	v_pk_mul_f32 v[114:115], v[98:99], v[114:115]
	v_pk_mul_f32 v[100:101], v[100:101], v[176:177] op_sel_hi:[1,0]
	v_max_f32_e32 v76, v76, v21
	v_max_f32_e32 v77, v77, v21
	v_pk_mul_f32 v[102:103], v[102:103], v[176:177] op_sel_hi:[1,0]
	v_max_f32_e32 v186, v186, v21
	v_max_f32_e32 v187, v187, v21
	v_cvt_pk_bf16_f32 v238, v250, v251
	v_cvt_pk_bf16_f32 v239, v212, v213
	v_pk_mul_f32 v[248:249], v[112:113], v[160:161]
	v_cvt_pk_bf16_f32 v224, v80, v81
	v_pk_mul_f32 v[194:195], v[114:115], v[162:163]
	v_cvt_pk_bf16_f32 v225, v188, v189
	v_pk_mul_f32 v[76:77], v[100:101], v[76:77] neg_lo:[1,0] neg_hi:[1,0]
	v_pk_mul_f32 v[186:187], v[102:103], v[186:187] neg_lo:[1,0] neg_hi:[1,0]
	v_pk_mul_f32 v[250:251], v[144:145], v[160:161]
	v_cvt_pk_bf16_f32 v232, v248, v249
	v_pk_mul_f32 v[212:213], v[146:147], v[162:163]
	v_cvt_pk_bf16_f32 v233, v194, v195
	v_pk_mul_f32 v[80:81], v[132:133], v[208:209]
	v_pk_mul_f32 v[116:117], v[100:101], v[116:117]
	v_cvt_pk_bf16_f32 v174, v76, v77
	v_pk_mul_f32 v[188:189], v[134:135], v[210:211]
	v_pk_mul_f32 v[118:119], v[102:103], v[118:119]
	v_cvt_pk_bf16_f32 v175, v186, v187
	ds_write_b128 v17, v[168:171] offset:0
	v_cvt_pk_bf16_f32 v244, v250, v251
	v_cvt_pk_bf16_f32 v245, v212, v213
	v_pk_mul_f32 v[248:249], v[116:117], v[164:165]
	v_cvt_pk_bf16_f32 v226, v80, v81
	v_pk_mul_f32 v[194:195], v[118:119], v[166:167]
	v_cvt_pk_bf16_f32 v227, v188, v189
	ds_write_b128 v18, v[172:175] offset:0
	ds_write_b128 v17, v[220:223] offset:2048
	v_pk_mul_f32 v[250:251], v[148:149], v[164:165]
	v_cvt_pk_bf16_f32 v234, v248, v249
	v_pk_mul_f32 v[212:213], v[150:151], v[166:167]
	v_cvt_pk_bf16_f32 v235, v194, v195
	ds_write_b128 v18, v[224:227] offset:2048
	ds_write_b128 v17, v[228:231] offset:4096
	v_cvt_pk_bf16_f32 v246, v250, v251
; #define LAS __attribute__((address_space(3)))
; __device__ __forceinline__ void phase_scan2(const Params& p, int l, LAS unsigned char* lds) {
;     ...
;             *(LAS float*)(sl + SC_WC + j * 4) = W;
; #pragma unroll
;             for (int q = 0; q < 4; ++q) *(LAS bf16_t*)(sl + SC_VP + (fr * 16 + 4 * fq + q) * 2) = vraw[q];
;             if (cnext >= 0) pload(cnext);
;             asm volatile("s_waitcnt lgkmcnt(0)" ::: "memory");
;             f32x4 AB = (f32x4){0.f, 0.f, 0.f, 0.f}, AKm = AB, RBm = AB, RKm = AB;
; #pragma unroll
;             for (int kk2 = 0; kk2 < 2; ++kk2) {
;                 const int fo = ((kk2 * 16 + fr) * 32 + fq * 8) * 2;
;                 const bf16x8 fa = *(LAS const bf16x8*)(sl + SC_AT + fo), fr_ = *(LAS const bf16x8*)(sl + SC_RT + fo);
;                 const bf16x8 fb = *(LAS const bf16x8*)(sc + 0 + fo), fk = *(LAS const bf16x8*)(sc + 2048 + fo);
;                 AB = __builtin_amdgcn_mfma_f32_16x16x32_bf16(fa, fb, AB, 0, 0, 0); AKm = __builtin_amdgcn_mfma_f32_16x16x32_bf16(fa, fk, AKm, 0, 0, 0);
;                 RBm = __builtin_amdgcn_mfma_f32_16x16x32_bf16(fr_, fb, RBm, 0, 0, 0); RKm = __builtin_amdgcn_mfma_f32_16x16x32_bf16(fr_, fk, RKm, 0, 0, 0);
;             }
; #pragma unroll
;             for (int r = 0; r < 4; ++r) { const int t = 4 * fq + r; const bool lo = fr < t, le = fr <= t;
;                 AB[r] = lo ? AB[r] : 0.f; AKm[r] = lo ? AKm[r] : 0.f; RBm[r] = le ? RBm[r] : 0.f; RKm[r] = le ? RKm[r] : 0.f; }
;             asm volatile("s_waitcnt lgkmcnt(0)" ::: "memory");
;             st_mat(sl + SC_AK, nullptr, nullptr, nullptr, AKm, fr, fq);
;             st_mat(sl + SC_RB, nullptr, nullptr, nullptr, RBm, fr, fq);
;             st_mat(sl + SC_RK, nullptr, nullptr, nullptr, RKm, fr, fq);
;             LAS unsigned char* mL = sc, *mLT = sc + 512, *mIL = sc + 1024, *mL2 = sc + 1536, *mL2T = sc + 2048, *mIL2T = sc + 2560, *mL4 = sc + 3072, *mL4T = sc + 3584, *mIL4T = sc + 4096, *mIL8T = sc + 4608, *mP1 = sc + 5120, *mP2 = sc + 5632;
;             st_mat(mL, mLT, nullptr, mIL, AB, fr, fq);
;             const f32x4 L2 = mm16(mL, mLT, fr, fq);      st_mat(mL2, mL2T, mIL2T, nullptr, L2, fr, fq);
;             const f32x4 L4 = mm16(mL2, mL2T, fr, fq);    const f32x4 P1 = mm16(mIL, mIL2T, fr, fq);
;             st_mat(mL4, mL4T, mIL4T, nullptr, L4, fr, fq); st_mat(mP1, nullptr, nullptr, nullptr, P1, fr, fq);
	v_cvt_pk_bf16_f32 v247, v212, v213
	ds_write_b128 v18, v[232:235] offset:4096
	ds_write_b128 v17, v[236:239] offset:6144
	ds_write_b128 v18, v[244:247] offset:6144
	s_mov_b32 exec_lo, 0x80008000
	s_mov_b32 exec_hi, 0x80008000
	ds_write_b128 v20, v[196:199] offset:0
	ds_write_b128 v20, v[200:203] offset:16
	ds_write_b128 v20, v[204:207] offset:32
	ds_write_b128 v20, v[208:211] offset:48
	s_mov_b64 exec, -1
	v_mfma_f32_16x16x32_bf16 v[92:95], v[168:171], v[236:239], 0
	v_mfma_f32_16x16x32_bf16 v[96:99], v[220:223], v[228:231], 0
	v_mfma_f32_16x16x32_bf16 v[100:103], v[220:223], v[236:239], 0
	v_mfma_f32_16x16x32_bf16 v[88:91], v[168:171], v[228:231], 0
	v_mfma_f32_16x16x32_bf16 v[92:95], v[172:175], v[244:247], v[92:95]
	v_mfma_f32_16x16x32_bf16 v[96:99], v[224:227], v[232:235], v[96:99]
	v_mfma_f32_16x16x32_bf16 v[100:103], v[224:227], v[244:247], v[100:103]
	v_mfma_f32_16x16x32_bf16 v[88:91], v[172:175], v[232:235], v[88:91]
	s_nop 4
	v_mul_f32_e32 v92, v30, v92
	v_mul_f32_e32 v93, v31, v93
	v_mul_f32_e32 v94, v32, v94
	v_mul_f32_e32 v95, v33, v95
	v_cvt_pk_bf16_f32 v76, v92, v93
	v_cvt_pk_bf16_f32 v77, v94, v95
	v_mul_f32_e32 v96, v34, v96
	v_mul_f32_e32 v97, v35, v97
	v_mul_f32_e32 v98, v36, v98
	v_mul_f32_e32 v99, v37, v99
	ds_write_b64 v19, v[76:77] offset:8192
	v_cvt_pk_bf16_f32 v76, v96, v97
	v_cvt_pk_bf16_f32 v77, v98, v99
	v_mul_f32_e32 v100, v34, v100
	v_mul_f32_e32 v101, v35, v101
	v_mul_f32_e32 v102, v36, v102
	v_mul_f32_e32 v103, v37, v103
	ds_write_b64 v19, v[76:77] offset:9216
	v_mul_f32_e32 v88, v30, v88
	v_mul_f32_e32 v89, v31, v89
	v_mul_f32_e32 v90, v32, v90
	v_mul_f32_e32 v91, v33, v91
	v_cvt_pk_bf16_f32 v76, v100, v101
	v_cvt_pk_bf16_f32 v77, v102, v103
	v_add_f32_e32 v248, v22, v88
	ds_write_b64 v19, v[76:77] offset:9728
	v_add_f32_e32 v249, v23, v89
	v_add_f32_e32 v250, v28, v90
	v_add_f32_e32 v251, v29, v91
	v_cvt_pk_bf16_f32 v76, v88, v89
	v_cvt_pk_bf16_f32 v77, v90, v91
	v_cvt_pk_bf16_f32 v80, v248, v249
	v_cvt_pk_bf16_f32 v81, v250, v251
	ds_write_b64 v15, v[76:77] offset:0
	ds_write_b64 v15, v[80:81] offset:512
	ds_read_b64_tr_b16 v[112:113], v14 offset:0
	ds_read_b64 v[114:115], v15 offset:0
	s_waitcnt lgkmcnt(0)
	v_mfma_f32_16x16x16_bf16 v[104:107], v[112:113], v[114:115], 0
	s_nop 7
	v_add_f32_e32 v248, v22, v104
	v_add_f32_e32 v249, v23, v105
	v_add_f32_e32 v250, v28, v106
	v_add_f32_e32 v251, v29, v107
	v_cvt_pk_bf16_f32 v76, v104, v105
	v_cvt_pk_bf16_f32 v77, v106, v107
	v_cvt_pk_bf16_f32 v80, v248, v249
	v_cvt_pk_bf16_f32 v81, v250, v251
	ds_write_b64 v15, v[76:77] offset:1024
	ds_write_b64 v15, v[80:81] offset:1536
	ds_read_b64_tr_b16 v[112:113], v14 offset:1024
	ds_read_b64 v[114:115], v15 offset:1024
	ds_read_b64_tr_b16 v[116:117], v14 offset:512
	ds_read_b64 v[118:119], v15 offset:1536
	s_waitcnt lgkmcnt(2)
	v_mfma_f32_16x16x16_bf16 v[104:107], v[112:113], v[114:115], 0
	s_waitcnt lgkmcnt(0)
	v_mfma_f32_16x16x16_bf16 v[108:111], v[116:117], v[118:119], 0
	s_nop 5
	v_cvt_pk_bf16_f32 v76, v104, v105
	v_cvt_pk_bf16_f32 v77, v106, v107
	v_add_f32_e32 v248, v22, v104
	v_add_f32_e32 v249, v23, v105
	v_add_f32_e32 v250, v28, v106
	v_add_f32_e32 v251, v29, v107
	ds_write_b64 v15, v[76:77] offset:0
	v_cvt_pk_bf16_f32 v80, v248, v249
	v_cvt_pk_bf16_f32 v81, v250, v251
	v_cvt_pk_bf16_f32 v76, v108, v109
	v_cvt_pk_bf16_f32 v77, v110, v111
	ds_write_b64 v15, v[80:81] offset:512
	ds_write_b64 v15, v[76:77] offset:1024
	ds_read_b64_tr_b16 v[112:113], v14 offset:0
	ds_read_b64 v[114:115], v15 offset:0
	ds_read_b64_tr_b16 v[116:117], v14 offset:1024
	ds_read_b64 v[118:119], v15 offset:512
	s_waitcnt lgkmcnt(2)
	v_mfma_f32_16x16x16_bf16 v[104:107], v[112:113], v[114:115], 0
	s_waitcnt lgkmcnt(0)
	v_mfma_f32_16x16x16_bf16 v[108:111], v[116:117], v[118:119], 0
	s_nop 5
	v_add_f32_e32 v248, v22, v104
	v_add_f32_e32 v249, v23, v105
	v_add_f32_e32 v250, v28, v106
	v_add_f32_e32 v251, v29, v107
	v_cvt_pk_bf16_f32 v80, v248, v249
	v_cvt_pk_bf16_f32 v81, v250, v251
	ds_write_b64 v15, v[80:81] offset:1536
	v_cvt_pk_bf16_f32 v76, v108, v109
	v_cvt_pk_bf16_f32 v77, v110, v111
	ds_write_b64 v15, v[76:77] offset:0
	ds_read_b64_tr_b16 v[112:113], v14 offset:0
	ds_read_b64 v[114:115], v15 offset:1536
	s_waitcnt lgkmcnt(0)
	v_mfma_f32_16x16x16_bf16 v[104:107], v[112:113], v[114:115], 0
	s_nop 7
	v_cvt_pk_bf16_f32 v76, v104, v105
	v_cvt_pk_bf16_f32 v77, v106, v107
	ds_write_b64 v19, v[76:77] offset:8704
	s_nop 0
.Lsc_p_skip:
	s_add_u32 s58, s58, 6
	s_sub_u32 s56, 69120, s56
	s_add_u32 s50, s50, 3072
	s_addc_u32 s51, s51, 0
	s_add_u32 s42, s42, 1
	s_waitcnt lgkmcnt(0)
	s_barrier
	s_cmp_le_u32 s42, 43
	s_cbranch_scc1 .Lsc_p_loop
	s_branch .Lsc_job_end
.Lsc_consumer:
	s_setprio 3
	v_and_b32_e32 v4, 7, v1
	s_lshr_b32 s1, s25, 2
	v_xor_b32_e32 v4, v4, v2
	s_mul_i32 s0, s1, 768
	v_lshlrev_b32_e32 v4, 4, v4
	v_and_b32_e32 v5, 3, v1
	v_lshl_add_u32 v156, v1, 7, v4
	v_lshrrev_b32_e32 v4, 2, v1
	v_add_u32_e32 v13, s0, v6
	v_lshl_add_u32 v4, v2, 2, v4
	s_add_u32 s53, s53, s1
	v_and_b32_e32 v158, 7, v4
	s_mul_i32 s0, s54, 4096
	v_xor_b32_e32 v158, v158, v5
	s_lshl_b32 s0, s0, 10
	v_lshlrev_b32_e32 v158, 4, v158
	s_lshl_b32 s14, s52, 7
	v_lshl_add_u32 v158, v4, 7, v158
	s_lshl_b32 s15, s53, 5
	s_add_u32 s0, s0, s14
	v_lshlrev_b32_e32 v157, 5, v2
	v_add_u32_e32 v158, 4096, v158
	v_lshlrev_b32_e32 v159, 12, v2
	s_add_u32 s0, s0, s15
	s_add_u32 s0, s0, 0x5000000
	v_mov_b32_e32 v8, 0
	v_mov_b32_e32 v116, 0
	v_mov_b32_e32 v9, 0
	v_mov_b32_e32 v117, 0
	v_mov_b32_e32 v10, 0
	v_mov_b32_e32 v118, 0
	v_mov_b32_e32 v11, 0
	v_mov_b32_e32 v119, 0
	v_mov_b32_e32 v16, 0
	v_mov_b32_e32 v120, 0
	v_mov_b32_e32 v17, 0
	v_mov_b32_e32 v121, 0
	v_mov_b32_e32 v18, 0
	v_mov_b32_e32 v122, 0
	v_mov_b32_e32 v19, 0
	v_mov_b32_e32 v123, 0
	v_mov_b32_e32 v20, 0
	v_mov_b32_e32 v124, 0
	v_mov_b32_e32 v21, 0
	v_mov_b32_e32 v125, 0
	v_mov_b32_e32 v22, 0
	v_mov_b32_e32 v126, 0
	v_mov_b32_e32 v23, 0
	v_mov_b32_e32 v127, 0
	v_mov_b32_e32 v24, 0
	v_mov_b32_e32 v128, 0
	v_mov_b32_e32 v25, 0
	v_mov_b32_e32 v129, 0
	v_mov_b32_e32 v26, 0
	v_mov_b32_e32 v130, 0
	v_mov_b32_e32 v27, 0
	v_mov_b32_e32 v131, 0
	v_xor_b32_e32 v162, 64, v156
	v_add_u32_e32 v157, 10752, v157
	v_xor_b32_e32 v163, 64, v158
	v_lshl_add_u32 v159, v1, 1, v159
	s_add_u32 s48, s74, s0
	s_addc_u32 s49, s75, 0
	s_mov_b32 s42, 0
	s_mov_b32 s58, 0
	s_mov_b32 s56, 0
	s_branch .Lsc_c_bar
; __device__ __forceinline__ void phase_scan2(const Params& p, int l, LAS unsigned char* lds) {
;     ...
;         auto consume = [&](int c, LAS const unsigned char* sl) {
;             const bf16x8 s0 = __builtin_bit_cast(bf16x8, (u32x4){pk_bf16(ST[0][0], ST[0][1]), pk_bf16(ST[0][2], ST[0][3]), pk_bf16(ST[1][0], ST[1][1]), pk_bf16(ST[1][2], ST[1][3])});
;             const bf16x8 s1 = __builtin_bit_cast(bf16x8, (u32x4){pk_bf16(ST[2][0], ST[2][1]), pk_bf16(ST[2][2], ST[2][3]), pk_bf16(ST[3][0], ST[3][1]), pk_bf16(ST[3][2], ST[3][3])});
;             const bf16x8 at0 = *(LAS const bf16x8*)(sl + SC_AT + (fr * 32 + fq * 8) * 2), at1 = *(LAS const bf16x8*)(sl + SC_AT + ((16 + fr) * 32 + fq * 8) * 2);
;             const bf16x8 rt0 = *(LAS const bf16x8*)(sl + SC_RT + (fr * 32 + fq * 8) * 2), rt1 = *(LAS const bf16x8*)(sl + SC_RT + ((16 + fr) * 32 + fq * 8) * 2);
;             const int mo = (fr * 16 + 4 * fq) * 2;
;             const bf16x8 vf = frag4(sl + SC_VP + mo), akf = frag4(sl + SC_AK + mo), xf = frag4(sl + SC_X + mo), rbf = frag4(sl + SC_RB + mo), rkf = frag4(sl + SC_RK + mo);
;             const f32x4 z = (f32x4){0.f, 0.f, 0.f, 0.f};
;             f32x4 g = __builtin_amdgcn_mfma_f32_16x16x32_bf16(at0, s0, z, 0, 0, 0);
;             g = __builtin_amdgcn_mfma_f32_16x16x32_bf16(at1, s1, g, 0, 0, 0);
;             g = __builtin_amdgcn_mfma_f32_16x16x32_bf16(akf, vf, g, 0, 0, 0);
;             const f32x4 sa = __builtin_amdgcn_mfma_f32_16x16x32_bf16(xf, cfrag(g), z, 0, 0, 0);
;             const bf16x8 saf = cfrag(sa);
;             f32x4 y = __builtin_amdgcn_mfma_f32_16x16x32_bf16(rt0, s0, z, 0, 0, 0);
;             y = __builtin_amdgcn_mfma_f32_16x16x32_bf16(rt1, s1, y, 0, 0, 0);
;             y = __builtin_amdgcn_mfma_f32_16x16x32_bf16(rbf, saf, y, 0, 0, 0);
;             y = __builtin_amdgcn_mfma_f32_16x16x32_bf16(rkf, vf, y, 0, 0, 0);
; #pragma unroll
;             for (int jt = 0; jt < 4; ++jt) {
;                 const f32x4 wc = *(LAS const f32x4*)(sl + SC_WC + (16 * jt + 4 * fq) * 4);
;                 const bf16x8 bb = frag4(sl + SC_BBT + ((16 * jt + fr) * SC_BS + 4 * fq) * 2), kb = frag4(sl + SC_KBT + ((16 * jt + fr) * SC_BS + 4 * fq) * 2);
;                 f32x4 acc = ST[jt];
;                 acc = __builtin_amdgcn_mfma_f32_16x16x32_bf16(bb, saf, acc, 0, 0, 0);
;                 acc = __builtin_amdgcn_mfma_f32_16x16x32_bf16(kb, vf, acc, 0, 0, 0);
.Lsc_c_loop:
	s_mov_b32 s57, s56
	s_cmp_ge_u32 s58, 256
	s_cbranch_scc1 .Lsc_c_itend
	v_add_u32_e32 v78, s57, v156
	v_add_u32_e32 v164, s57, v162
	ds_read_b128 v[36:39], v78 offset:0
	ds_read_b128 v[44:47], v78 offset:2048
	v_add_u32_e32 v80, s57, v13
	ds_read_b128 v[40:43], v164 offset:0
	v_add_u32_e32 v161, s57, v7
	ds_read_b128 v[48:51], v164 offset:2048
	ds_read_b64 v[60:61], v80 offset:10240
	ds_read_b64_tr_b16 v[14:15], v161 offset:8192
	ds_read_b64_tr_b16 v[52:53], v161 offset:8704
	v_add_u32_e32 v82, s57, v158
	ds_read_b64_tr_b16 v[56:57], v161 offset:9728
	ds_read_b64_tr_b16 v[58:59], v161 offset:9216
	v_add_u32_e32 v165, s57, v163
	ds_read_b64_tr_b16 v[88:89], v82 offset:2048
	ds_read_b64_tr_b16 v[92:93], v82 offset:2056
	v_add_u32_e32 v81, s57, v157
	ds_read_b64_tr_b16 v[96:97], v165 offset:2048
	v_cvt_pk_bf16_f32 v28, v8, v9
	v_cvt_pk_bf16_f32 v29, v10, v11
	v_cvt_pk_bf16_f32 v30, v16, v17
	v_cvt_pk_bf16_f32 v31, v18, v19
	v_cvt_pk_bf16_f32 v32, v20, v21
	v_cvt_pk_bf16_f32 v33, v22, v23
	v_cvt_pk_bf16_f32 v34, v24, v25
	v_cvt_pk_bf16_f32 v35, v26, v27
	ds_read_b64_tr_b16 v[100:101], v165 offset:2056
	s_waitcnt lgkmcnt(12)
	v_mfma_f32_16x16x32_bf16 v[104:107], v[36:39], v[28:31], 0
	ds_read_b128 v[36:39], v78 offset:11520
	s_waitcnt lgkmcnt(12)
	v_mfma_f32_16x16x32_bf16 v[112:115], v[44:47], v[28:31], 0
	ds_read_b128 v[44:47], v78 offset:13568
	s_waitcnt lgkmcnt(12)
	v_mfma_f32_16x16x32_bf16 v[104:107], v[40:43], v[32:35], v[104:107]
	ds_read_b128 v[40:43], v164 offset:11520
	s_waitcnt lgkmcnt(12)
	v_mfma_f32_16x16x32_bf16 v[112:115], v[48:51], v[32:35], v[112:115]
	ds_read_b128 v[48:51], v164 offset:13568
	s_waitcnt lgkmcnt(11)
	s_nop 0
	v_mfma_f32_16x16x16_bf16 v[104:107], v[14:15], v[60:61], v[104:107]
	ds_read_b64_tr_b16 v[90:91], v82 offset:0
	ds_read_b64_tr_b16 v[94:95], v82 offset:8
	ds_read_b64_tr_b16 v[98:99], v165 offset:0
	ds_read_b64_tr_b16 v[102:103], v165 offset:8
	s_nop 3
	v_cvt_pk_bf16_f32 v54, v104, v105
	v_cvt_pk_bf16_f32 v55, v106, v107
	s_waitcnt lgkmcnt(14)
	s_nop 0
	v_mfma_f32_16x16x16_bf16 v[108:111], v[52:53], v[54:55], 0
	s_nop 7
	v_cvt_pk_bf16_f32 v62, v108, v109
	v_cvt_pk_bf16_f32 v63, v110, v111
	s_waitcnt lgkmcnt(0)
	s_nop 0
	v_mfma_f32_16x16x32_bf16 v[112:115], v[56:59], v[60:63], v[112:115]
	v_mfma_f32_16x16x32_bf16 v[8:11], v[88:91], v[60:63], v[8:11]
	v_mfma_f32_16x16x32_bf16 v[16:19], v[92:95], v[60:63], v[16:19]
	v_mfma_f32_16x16x32_bf16 v[20:23], v[96:99], v[60:63], v[20:23]
	v_mfma_f32_16x16x32_bf16 v[24:27], v[100:103], v[60:63], v[24:27]
	ds_read_b128 v[64:67], v81 offset:0
	ds_read_b128 v[68:71], v81 offset:16
	ds_read_b128 v[72:75], v81 offset:128
	ds_read_b128 v[84:87], v81 offset:144
	v_cvt_pk_bf16_f32 v160, v112, v112
	ds_read_b64 v[60:61], v80 offset:21760
	global_store_short v159, v160, s[48:49] offset:0
	v_cvt_pk_bf16_f32 v160, v113, v113
	global_store_short v159, v160, s[48:49] offset:1024
	v_cvt_pk_bf16_f32 v160, v114, v114
	global_store_short v159, v160, s[48:49] offset:2048
	v_cvt_pk_bf16_f32 v160, v115, v115
	global_store_short v159, v160, s[48:49] offset:3072
	s_waitcnt lgkmcnt(1)
	s_add_u32 s58, s58, 1
	s_add_u32 s48, s48, 0x4000
	s_addc_u32 s49, s49, 0
	v_pk_mul_f32 v[8:9], v[8:9], v[64:65]
	v_pk_mul_f32 v[10:11], v[10:11], v[66:67]
	v_pk_mul_f32 v[16:17], v[16:17], v[68:69]
	v_pk_mul_f32 v[18:19], v[18:19], v[70:71]
	v_pk_mul_f32 v[20:21], v[20:21], v[72:73]
	v_pk_mul_f32 v[22:23], v[22:23], v[74:75]
	v_pk_mul_f32 v[24:25], v[24:25], v[84:85]
	v_pk_mul_f32 v[26:27], v[26:27], v[86:87]
	s_add_u32 s57, s57, 11520
	s_cmp_ge_u32 s58, 256
	s_cbranch_scc1 .Lsc_c_itend
	v_add_u32_e32 v161, s57, v7
	v_add_u32_e32 v82, s57, v158
	ds_read_b64_tr_b16 v[14:15], v161 offset:8192
	ds_read_b64_tr_b16 v[52:53], v161 offset:8704
	ds_read_b64_tr_b16 v[56:57], v161 offset:9728
	ds_read_b64_tr_b16 v[58:59], v161 offset:9216
	v_add_u32_e32 v165, s57, v163
	ds_read_b64_tr_b16 v[88:89], v82 offset:2048
	ds_read_b64_tr_b16 v[92:93], v82 offset:2056
	v_add_u32_e32 v78, s57, v156
	v_add_u32_e32 v80, s57, v13
	v_add_u32_e32 v81, s57, v157
	v_add_u32_e32 v164, s57, v162
	ds_read_b64_tr_b16 v[96:97], v165 offset:2048
	v_cvt_pk_bf16_f32 v28, v8, v9
	v_cvt_pk_bf16_f32 v29, v10, v11
	v_cvt_pk_bf16_f32 v30, v16, v17
	v_cvt_pk_bf16_f32 v31, v18, v19
	v_cvt_pk_bf16_f32 v32, v20, v21
	v_cvt_pk_bf16_f32 v33, v22, v23
	v_cvt_pk_bf16_f32 v34, v24, v25
	v_cvt_pk_bf16_f32 v35, v26, v27
	ds_read_b64_tr_b16 v[100:101], v165 offset:2056
	s_waitcnt lgkmcnt(12)
	v_mfma_f32_16x16x32_bf16 v[104:107], v[36:39], v[28:31], 0
	ds_read_b128 v[36:39], v78 offset:11520
	s_waitcnt lgkmcnt(12)
	v_mfma_f32_16x16x32_bf16 v[112:115], v[44:47], v[28:31], 0
	ds_read_b128 v[44:47], v78 offset:13568
	s_waitcnt lgkmcnt(12)
	v_mfma_f32_16x16x32_bf16 v[104:107], v[40:43], v[32:35], v[104:107]
	ds_read_b128 v[40:43], v164 offset:11520
	s_waitcnt lgkmcnt(12)
	v_mfma_f32_16x16x32_bf16 v[112:115], v[48:51], v[32:35], v[112:115]
	ds_read_b128 v[48:51], v164 offset:13568
	s_waitcnt lgkmcnt(11)
	s_nop 0
	v_mfma_f32_16x16x16_bf16 v[104:107], v[14:15], v[60:61], v[104:107]
	ds_read_b64_tr_b16 v[90:91], v82 offset:0
	ds_read_b64_tr_b16 v[94:95], v82 offset:8
	ds_read_b64_tr_b16 v[98:99], v165 offset:0
	ds_read_b64_tr_b16 v[102:103], v165 offset:8
	s_nop 3
	v_cvt_pk_bf16_f32 v54, v104, v105
	v_cvt_pk_bf16_f32 v55, v106, v107
	s_waitcnt lgkmcnt(14)
	s_nop 0
	v_mfma_f32_16x16x16_bf16 v[108:111], v[52:53], v[54:55], 0
	s_nop 7
	v_cvt_pk_bf16_f32 v62, v108, v109
	v_cvt_pk_bf16_f32 v63, v110, v111
	s_waitcnt lgkmcnt(0)
	s_nop 0
	v_mfma_f32_16x16x32_bf16 v[112:115], v[56:59], v[60:63], v[112:115]
	v_mfma_f32_16x16x32_bf16 v[8:11], v[88:91], v[60:63], v[8:11]
	v_mfma_f32_16x16x32_bf16 v[16:19], v[92:95], v[60:63], v[16:19]
	v_mfma_f32_16x16x32_bf16 v[20:23], v[96:99], v[60:63], v[20:23]
	v_mfma_f32_16x16x32_bf16 v[24:27], v[100:103], v[60:63], v[24:27]
	ds_read_b128 v[64:67], v81 offset:0
	ds_read_b128 v[68:71], v81 offset:16
	ds_read_b128 v[72:75], v81 offset:128
	ds_read_b128 v[84:87], v81 offset:144
	v_cvt_pk_bf16_f32 v160, v112, v112
	ds_read_b64 v[60:61], v80 offset:21760
	global_store_short v159, v160, s[48:49] offset:0
	v_cvt_pk_bf16_f32 v160, v113, v113
	global_store_short v159, v160, s[48:49] offset:1024
	v_cvt_pk_bf16_f32 v160, v114, v114
	global_store_short v159, v160, s[48:49] offset:2048
	v_cvt_pk_bf16_f32 v160, v115, v115
	global_store_short v159, v160, s[48:49] offset:3072
	s_waitcnt lgkmcnt(1)
	s_add_u32 s58, s58, 1
	s_add_u32 s48, s48, 0x4000
	s_addc_u32 s49, s49, 0
	v_pk_mul_f32 v[8:9], v[8:9], v[64:65]
	v_pk_mul_f32 v[10:11], v[10:11], v[66:67]
	v_pk_mul_f32 v[16:17], v[16:17], v[68:69]
	v_pk_mul_f32 v[18:19], v[18:19], v[70:71]
	v_pk_mul_f32 v[20:21], v[20:21], v[72:73]
	v_pk_mul_f32 v[22:23], v[22:23], v[74:75]
	v_pk_mul_f32 v[24:25], v[24:25], v[84:85]
	v_pk_mul_f32 v[26:27], v[26:27], v[86:87]
	s_add_u32 s57, s57, 11520
	s_cmp_ge_u32 s58, 256
	s_cbranch_scc1 .Lsc_c_itend
; __device__ __forceinline__ void phase_scan2(const Params& p, int l, LAS unsigned char* lds) {
;     ...
;         auto consume = [&](int c, LAS const unsigned char* sl) {
;             const bf16x8 s0 = __builtin_bit_cast(bf16x8, (u32x4){pk_bf16(ST[0][0], ST[0][1]), pk_bf16(ST[0][2], ST[0][3]), pk_bf16(ST[1][0], ST[1][1]), pk_bf16(ST[1][2], ST[1][3])});
;             const bf16x8 s1 = __builtin_bit_cast(bf16x8, (u32x4){pk_bf16(ST[2][0], ST[2][1]), pk_bf16(ST[2][2], ST[2][3]), pk_bf16(ST[3][0], ST[3][1]), pk_bf16(ST[3][2], ST[3][3])});
;             const bf16x8 at0 = *(LAS const bf16x8*)(sl + SC_AT + (fr * 32 + fq * 8) * 2), at1 = *(LAS const bf16x8*)(sl + SC_AT + ((16 + fr) * 32 + fq * 8) * 2);
;             const bf16x8 rt0 = *(LAS const bf16x8*)(sl + SC_RT + (fr * 32 + fq * 8) * 2), rt1 = *(LAS const bf16x8*)(sl + SC_RT + ((16 + fr) * 32 + fq * 8) * 2);
;             const int mo = (fr * 16 + 4 * fq) * 2;
;             const bf16x8 vf = frag4(sl + SC_VP + mo), akf = frag4(sl + SC_AK + mo), xf = frag4(sl + SC_X + mo), rbf = frag4(sl + SC_RB + mo), rkf = frag4(sl + SC_RK + mo);
;             const f32x4 z = (f32x4){0.f, 0.f, 0.f, 0.f};
;             f32x4 g = __builtin_amdgcn_mfma_f32_16x16x32_bf16(at0, s0, z, 0, 0, 0);
;             g = __builtin_amdgcn_mfma_f32_16x16x32_bf16(at1, s1, g, 0, 0, 0);
;             g = __builtin_amdgcn_mfma_f32_16x16x32_bf16(akf, vf, g, 0, 0, 0);
;             const f32x4 sa = __builtin_amdgcn_mfma_f32_16x16x32_bf16(xf, cfrag(g), z, 0, 0, 0);
;             const bf16x8 saf = cfrag(sa);
;             f32x4 y = __builtin_amdgcn_mfma_f32_16x16x32_bf16(rt0, s0, z, 0, 0, 0);
;             y = __builtin_amdgcn_mfma_f32_16x16x32_bf16(rt1, s1, y, 0, 0, 0);
;             y = __builtin_amdgcn_mfma_f32_16x16x32_bf16(rbf, saf, y, 0, 0, 0);
;             y = __builtin_amdgcn_mfma_f32_16x16x32_bf16(rkf, vf, y, 0, 0, 0);
; #pragma unroll
;             for (int jt = 0; jt < 4; ++jt) {
;                 const f32x4 wc = *(LAS const f32x4*)(sl + SC_WC + (16 * jt + 4 * fq) * 4);
;                 const bf16x8 bb = frag4(sl + SC_BBT + ((16 * jt + fr) * SC_BS + 4 * fq) * 2), kb = frag4(sl + SC_KBT + ((16 * jt + fr) * SC_BS + 4 * fq) * 2);
;                 f32x4 acc = ST[jt];
;                 acc = __builtin_amdgcn_mfma_f32_16x16x32_bf16(bb, saf, acc, 0, 0, 0);
;                 acc = __builtin_amdgcn_mfma_f32_16x16x32_bf16(kb, vf, acc, 0, 0, 0);
	v_add_u32_e32 v161, s57, v7
	v_add_u32_e32 v82, s57, v158
	ds_read_b64_tr_b16 v[14:15], v161 offset:8192
	ds_read_b64_tr_b16 v[52:53], v161 offset:8704
	ds_read_b64_tr_b16 v[56:57], v161 offset:9728
	ds_read_b64_tr_b16 v[58:59], v161 offset:9216
	v_add_u32_e32 v165, s57, v163
	ds_read_b64_tr_b16 v[88:89], v82 offset:2048
	ds_read_b64_tr_b16 v[92:93], v82 offset:2056
	v_add_u32_e32 v78, s57, v156
	v_add_u32_e32 v80, s57, v13
	v_add_u32_e32 v81, s57, v157
	v_add_u32_e32 v164, s57, v162
	ds_read_b64_tr_b16 v[96:97], v165 offset:2048
	v_cvt_pk_bf16_f32 v28, v8, v9
	v_cvt_pk_bf16_f32 v29, v10, v11
	v_cvt_pk_bf16_f32 v30, v16, v17
	v_cvt_pk_bf16_f32 v31, v18, v19
	v_cvt_pk_bf16_f32 v32, v20, v21
	v_cvt_pk_bf16_f32 v33, v22, v23
	v_cvt_pk_bf16_f32 v34, v24, v25
	v_cvt_pk_bf16_f32 v35, v26, v27
	ds_read_b64_tr_b16 v[100:101], v165 offset:2056
	s_waitcnt lgkmcnt(12)
	v_mfma_f32_16x16x32_bf16 v[104:107], v[36:39], v[28:31], 0
	ds_read_b128 v[36:39], v78 offset:11520
	s_waitcnt lgkmcnt(12)
	v_mfma_f32_16x16x32_bf16 v[112:115], v[44:47], v[28:31], 0
	ds_read_b128 v[44:47], v78 offset:13568
	s_waitcnt lgkmcnt(12)
	v_mfma_f32_16x16x32_bf16 v[104:107], v[40:43], v[32:35], v[104:107]
	ds_read_b128 v[40:43], v164 offset:11520
	s_waitcnt lgkmcnt(12)
	v_mfma_f32_16x16x32_bf16 v[112:115], v[48:51], v[32:35], v[112:115]
	ds_read_b128 v[48:51], v164 offset:13568
	s_waitcnt lgkmcnt(11)
	s_nop 0
	v_mfma_f32_16x16x16_bf16 v[104:107], v[14:15], v[60:61], v[104:107]
	ds_read_b64_tr_b16 v[90:91], v82 offset:0
	ds_read_b64_tr_b16 v[94:95], v82 offset:8
	ds_read_b64_tr_b16 v[98:99], v165 offset:0
	ds_read_b64_tr_b16 v[102:103], v165 offset:8
	s_nop 3
	v_cvt_pk_bf16_f32 v54, v104, v105
	v_cvt_pk_bf16_f32 v55, v106, v107
	s_waitcnt lgkmcnt(14)
	s_nop 0
	v_mfma_f32_16x16x16_bf16 v[108:111], v[52:53], v[54:55], 0
	s_nop 7
	v_cvt_pk_bf16_f32 v62, v108, v109
	v_cvt_pk_bf16_f32 v63, v110, v111
	s_waitcnt lgkmcnt(0)
	s_nop 0
	v_mfma_f32_16x16x32_bf16 v[112:115], v[56:59], v[60:63], v[112:115]
	v_mfma_f32_16x16x32_bf16 v[8:11], v[88:91], v[60:63], v[8:11]
	v_mfma_f32_16x16x32_bf16 v[16:19], v[92:95], v[60:63], v[16:19]
	v_mfma_f32_16x16x32_bf16 v[20:23], v[96:99], v[60:63], v[20:23]
	v_mfma_f32_16x16x32_bf16 v[24:27], v[100:103], v[60:63], v[24:27]
	ds_read_b128 v[64:67], v81 offset:0
	ds_read_b128 v[68:71], v81 offset:16
	ds_read_b128 v[72:75], v81 offset:128
	ds_read_b128 v[84:87], v81 offset:144
	v_cvt_pk_bf16_f32 v160, v112, v112
	ds_read_b64 v[60:61], v80 offset:21760
	global_store_short v159, v160, s[48:49] offset:0
	v_cvt_pk_bf16_f32 v160, v113, v113
	global_store_short v159, v160, s[48:49] offset:1024
	v_cvt_pk_bf16_f32 v160, v114, v114
	global_store_short v159, v160, s[48:49] offset:2048
	v_cvt_pk_bf16_f32 v160, v115, v115
	global_store_short v159, v160, s[48:49] offset:3072
	s_waitcnt lgkmcnt(1)
	s_add_u32 s58, s58, 1
	s_add_u32 s48, s48, 0x4000
	s_addc_u32 s49, s49, 0
	v_pk_mul_f32 v[8:9], v[8:9], v[64:65]
	v_pk_mul_f32 v[10:11], v[10:11], v[66:67]
	v_pk_mul_f32 v[16:17], v[16:17], v[68:69]
	v_pk_mul_f32 v[18:19], v[18:19], v[70:71]
	v_pk_mul_f32 v[20:21], v[20:21], v[72:73]
	v_pk_mul_f32 v[22:23], v[22:23], v[74:75]
	v_pk_mul_f32 v[24:25], v[24:25], v[84:85]
	v_pk_mul_f32 v[26:27], v[26:27], v[86:87]
	s_add_u32 s57, s57, 11520
	s_cmp_ge_u32 s58, 256
	s_cbranch_scc1 .Lsc_c_itend
	v_add_u32_e32 v161, s57, v7
	v_add_u32_e32 v82, s57, v158
	ds_read_b64_tr_b16 v[14:15], v161 offset:8192
	ds_read_b64_tr_b16 v[52:53], v161 offset:8704
	ds_read_b64_tr_b16 v[56:57], v161 offset:9728
	ds_read_b64_tr_b16 v[58:59], v161 offset:9216
	v_add_u32_e32 v165, s57, v163
	ds_read_b64_tr_b16 v[88:89], v82 offset:2048
	ds_read_b64_tr_b16 v[92:93], v82 offset:2056
	v_add_u32_e32 v78, s57, v156
	v_add_u32_e32 v80, s57, v13
	v_add_u32_e32 v81, s57, v157
	v_add_u32_e32 v164, s57, v162
	ds_read_b64_tr_b16 v[96:97], v165 offset:2048
	v_cvt_pk_bf16_f32 v28, v8, v9
	v_cvt_pk_bf16_f32 v29, v10, v11
	v_cvt_pk_bf16_f32 v30, v16, v17
	v_cvt_pk_bf16_f32 v31, v18, v19
	v_cvt_pk_bf16_f32 v32, v20, v21
	v_cvt_pk_bf16_f32 v33, v22, v23
	v_cvt_pk_bf16_f32 v34, v24, v25
	v_cvt_pk_bf16_f32 v35, v26, v27
	ds_read_b64_tr_b16 v[100:101], v165 offset:2056
	s_waitcnt lgkmcnt(12)
	v_mfma_f32_16x16x32_bf16 v[104:107], v[36:39], v[28:31], 0
	ds_read_b128 v[36:39], v78 offset:11520
	s_waitcnt lgkmcnt(12)
	v_mfma_f32_16x16x32_bf16 v[112:115], v[44:47], v[28:31], 0
	ds_read_b128 v[44:47], v78 offset:13568
	s_waitcnt lgkmcnt(12)
	v_mfma_f32_16x16x32_bf16 v[104:107], v[40:43], v[32:35], v[104:107]
	ds_read_b128 v[40:43], v164 offset:11520
	s_waitcnt lgkmcnt(12)
	v_mfma_f32_16x16x32_bf16 v[112:115], v[48:51], v[32:35], v[112:115]
	ds_read_b128 v[48:51], v164 offset:13568
	s_waitcnt lgkmcnt(11)
	s_nop 0
	v_mfma_f32_16x16x16_bf16 v[104:107], v[14:15], v[60:61], v[104:107]
	ds_read_b64_tr_b16 v[90:91], v82 offset:0
	ds_read_b64_tr_b16 v[94:95], v82 offset:8
	ds_read_b64_tr_b16 v[98:99], v165 offset:0
	ds_read_b64_tr_b16 v[102:103], v165 offset:8
	s_nop 3
	v_cvt_pk_bf16_f32 v54, v104, v105
	v_cvt_pk_bf16_f32 v55, v106, v107
	s_waitcnt lgkmcnt(14)
	s_nop 0
	v_mfma_f32_16x16x16_bf16 v[108:111], v[52:53], v[54:55], 0
	s_nop 7
	v_cvt_pk_bf16_f32 v62, v108, v109
	v_cvt_pk_bf16_f32 v63, v110, v111
	s_waitcnt lgkmcnt(0)
	s_nop 0
	v_mfma_f32_16x16x32_bf16 v[112:115], v[56:59], v[60:63], v[112:115]
	v_mfma_f32_16x16x32_bf16 v[8:11], v[88:91], v[60:63], v[8:11]
	v_mfma_f32_16x16x32_bf16 v[16:19], v[92:95], v[60:63], v[16:19]
	v_mfma_f32_16x16x32_bf16 v[20:23], v[96:99], v[60:63], v[20:23]
	v_mfma_f32_16x16x32_bf16 v[24:27], v[100:103], v[60:63], v[24:27]
	ds_read_b128 v[64:67], v81 offset:0
	ds_read_b128 v[68:71], v81 offset:16
	ds_read_b128 v[72:75], v81 offset:128
	ds_read_b128 v[84:87], v81 offset:144
	v_cvt_pk_bf16_f32 v160, v112, v112
	ds_read_b64 v[60:61], v80 offset:21760
	global_store_short v159, v160, s[48:49] offset:0
	v_cvt_pk_bf16_f32 v160, v113, v113
	global_store_short v159, v160, s[48:49] offset:1024
	v_cvt_pk_bf16_f32 v160, v114, v114
	global_store_short v159, v160, s[48:49] offset:2048
	v_cvt_pk_bf16_f32 v160, v115, v115
	global_store_short v159, v160, s[48:49] offset:3072
	s_waitcnt lgkmcnt(1)
	s_add_u32 s58, s58, 1
	s_add_u32 s48, s48, 0x4000
	s_addc_u32 s49, s49, 0
	v_pk_mul_f32 v[8:9], v[8:9], v[64:65]
	v_pk_mul_f32 v[10:11], v[10:11], v[66:67]
	v_pk_mul_f32 v[16:17], v[16:17], v[68:69]
	v_pk_mul_f32 v[18:19], v[18:19], v[70:71]
	v_pk_mul_f32 v[20:21], v[20:21], v[72:73]
	v_pk_mul_f32 v[22:23], v[22:23], v[74:75]
	v_pk_mul_f32 v[24:25], v[24:25], v[84:85]
	v_pk_mul_f32 v[26:27], v[26:27], v[86:87]
	s_add_u32 s57, s57, 11520
	s_cmp_ge_u32 s58, 256
	s_cbranch_scc1 .Lsc_c_itend
; __device__ __forceinline__ void phase_scan2(const Params& p, int l, LAS unsigned char* lds) {
;     ...
;         auto consume = [&](int c, LAS const unsigned char* sl) {
;             const bf16x8 s0 = __builtin_bit_cast(bf16x8, (u32x4){pk_bf16(ST[0][0], ST[0][1]), pk_bf16(ST[0][2], ST[0][3]), pk_bf16(ST[1][0], ST[1][1]), pk_bf16(ST[1][2], ST[1][3])});
;             const bf16x8 s1 = __builtin_bit_cast(bf16x8, (u32x4){pk_bf16(ST[2][0], ST[2][1]), pk_bf16(ST[2][2], ST[2][3]), pk_bf16(ST[3][0], ST[3][1]), pk_bf16(ST[3][2], ST[3][3])});
;             const bf16x8 at0 = *(LAS const bf16x8*)(sl + SC_AT + (fr * 32 + fq * 8) * 2), at1 = *(LAS const bf16x8*)(sl + SC_AT + ((16 + fr) * 32 + fq * 8) * 2);
;             const bf16x8 rt0 = *(LAS const bf16x8*)(sl + SC_RT + (fr * 32 + fq * 8) * 2), rt1 = *(LAS const bf16x8*)(sl + SC_RT + ((16 + fr) * 32 + fq * 8) * 2);
;             const int mo = (fr * 16 + 4 * fq) * 2;
;             const bf16x8 vf = frag4(sl + SC_VP + mo), akf = frag4(sl + SC_AK + mo), xf = frag4(sl + SC_X + mo), rbf = frag4(sl + SC_RB + mo), rkf = frag4(sl + SC_RK + mo);
;             const f32x4 z = (f32x4){0.f, 0.f, 0.f, 0.f};
;             f32x4 g = __builtin_amdgcn_mfma_f32_16x16x32_bf16(at0, s0, z, 0, 0, 0);
;             g = __builtin_amdgcn_mfma_f32_16x16x32_bf16(at1, s1, g, 0, 0, 0);
;             g = __builtin_amdgcn_mfma_f32_16x16x32_bf16(akf, vf, g, 0, 0, 0);
;             const f32x4 sa = __builtin_amdgcn_mfma_f32_16x16x32_bf16(xf, cfrag(g), z, 0, 0, 0);
;             const bf16x8 saf = cfrag(sa);
;             f32x4 y = __builtin_amdgcn_mfma_f32_16x16x32_bf16(rt0, s0, z, 0, 0, 0);
;             y = __builtin_amdgcn_mfma_f32_16x16x32_bf16(rt1, s1, y, 0, 0, 0);
;             y = __builtin_amdgcn_mfma_f32_16x16x32_bf16(rbf, saf, y, 0, 0, 0);
;             y = __builtin_amdgcn_mfma_f32_16x16x32_bf16(rkf, vf, y, 0, 0, 0);
; #pragma unroll
;             for (int jt = 0; jt < 4; ++jt) {
;                 const f32x4 wc = *(LAS const f32x4*)(sl + SC_WC + (16 * jt + 4 * fq) * 4);
;                 const bf16x8 bb = frag4(sl + SC_BBT + ((16 * jt + fr) * SC_BS + 4 * fq) * 2), kb = frag4(sl + SC_KBT + ((16 * jt + fr) * SC_BS + 4 * fq) * 2);
;                 f32x4 acc = ST[jt];
;                 acc = __builtin_amdgcn_mfma_f32_16x16x32_bf16(bb, saf, acc, 0, 0, 0);
;                 acc = __builtin_amdgcn_mfma_f32_16x16x32_bf16(kb, vf, acc, 0, 0, 0);
	v_add_u32_e32 v161, s57, v7
	v_add_u32_e32 v82, s57, v158
	ds_read_b64_tr_b16 v[14:15], v161 offset:8192
	ds_read_b64_tr_b16 v[52:53], v161 offset:8704
	ds_read_b64_tr_b16 v[56:57], v161 offset:9728
	ds_read_b64_tr_b16 v[58:59], v161 offset:9216
	v_add_u32_e32 v165, s57, v163
	ds_read_b64_tr_b16 v[88:89], v82 offset:2048
	ds_read_b64_tr_b16 v[92:93], v82 offset:2056
	v_add_u32_e32 v78, s57, v156
	v_add_u32_e32 v80, s57, v13
	v_add_u32_e32 v81, s57, v157
	v_add_u32_e32 v164, s57, v162
	ds_read_b64_tr_b16 v[96:97], v165 offset:2048
	v_cvt_pk_bf16_f32 v28, v8, v9
	v_cvt_pk_bf16_f32 v29, v10, v11
	v_cvt_pk_bf16_f32 v30, v16, v17
	v_cvt_pk_bf16_f32 v31, v18, v19
	v_cvt_pk_bf16_f32 v32, v20, v21
	v_cvt_pk_bf16_f32 v33, v22, v23
	v_cvt_pk_bf16_f32 v34, v24, v25
	v_cvt_pk_bf16_f32 v35, v26, v27
	ds_read_b64_tr_b16 v[100:101], v165 offset:2056
	s_waitcnt lgkmcnt(12)
	v_mfma_f32_16x16x32_bf16 v[104:107], v[36:39], v[28:31], 0
	ds_read_b128 v[36:39], v78 offset:11520
	s_waitcnt lgkmcnt(12)
	v_mfma_f32_16x16x32_bf16 v[112:115], v[44:47], v[28:31], 0
	ds_read_b128 v[44:47], v78 offset:13568
	s_waitcnt lgkmcnt(12)
	v_mfma_f32_16x16x32_bf16 v[104:107], v[40:43], v[32:35], v[104:107]
	ds_read_b128 v[40:43], v164 offset:11520
	s_waitcnt lgkmcnt(12)
	v_mfma_f32_16x16x32_bf16 v[112:115], v[48:51], v[32:35], v[112:115]
	ds_read_b128 v[48:51], v164 offset:13568
	s_waitcnt lgkmcnt(11)
	s_nop 0
	v_mfma_f32_16x16x16_bf16 v[104:107], v[14:15], v[60:61], v[104:107]
	ds_read_b64_tr_b16 v[90:91], v82 offset:0
	ds_read_b64_tr_b16 v[94:95], v82 offset:8
	ds_read_b64_tr_b16 v[98:99], v165 offset:0
	ds_read_b64_tr_b16 v[102:103], v165 offset:8
	s_nop 3
	v_cvt_pk_bf16_f32 v54, v104, v105
	v_cvt_pk_bf16_f32 v55, v106, v107
	s_waitcnt lgkmcnt(14)
	s_nop 0
	v_mfma_f32_16x16x16_bf16 v[108:111], v[52:53], v[54:55], 0
	s_nop 7
	v_cvt_pk_bf16_f32 v62, v108, v109
	v_cvt_pk_bf16_f32 v63, v110, v111
	s_waitcnt lgkmcnt(0)
	s_nop 0
	v_mfma_f32_16x16x32_bf16 v[112:115], v[56:59], v[60:63], v[112:115]
	v_mfma_f32_16x16x32_bf16 v[8:11], v[88:91], v[60:63], v[8:11]
	v_mfma_f32_16x16x32_bf16 v[16:19], v[92:95], v[60:63], v[16:19]
	v_mfma_f32_16x16x32_bf16 v[20:23], v[96:99], v[60:63], v[20:23]
	v_mfma_f32_16x16x32_bf16 v[24:27], v[100:103], v[60:63], v[24:27]
	ds_read_b128 v[64:67], v81 offset:0
	ds_read_b128 v[68:71], v81 offset:16
	ds_read_b128 v[72:75], v81 offset:128
	ds_read_b128 v[84:87], v81 offset:144
	v_cvt_pk_bf16_f32 v160, v112, v112
	ds_read_b64 v[60:61], v80 offset:21760
	global_store_short v159, v160, s[48:49] offset:0
	v_cvt_pk_bf16_f32 v160, v113, v113
	global_store_short v159, v160, s[48:49] offset:1024
	v_cvt_pk_bf16_f32 v160, v114, v114
	global_store_short v159, v160, s[48:49] offset:2048
	v_cvt_pk_bf16_f32 v160, v115, v115
	global_store_short v159, v160, s[48:49] offset:3072
	s_waitcnt lgkmcnt(1)
	s_add_u32 s58, s58, 1
	s_add_u32 s48, s48, 0x4000
	s_addc_u32 s49, s49, 0
	v_pk_mul_f32 v[8:9], v[8:9], v[64:65]
	v_pk_mul_f32 v[10:11], v[10:11], v[66:67]
	v_pk_mul_f32 v[16:17], v[16:17], v[68:69]
	v_pk_mul_f32 v[18:19], v[18:19], v[70:71]
	v_pk_mul_f32 v[20:21], v[20:21], v[72:73]
	v_pk_mul_f32 v[22:23], v[22:23], v[74:75]
	v_pk_mul_f32 v[24:25], v[24:25], v[84:85]
	v_pk_mul_f32 v[26:27], v[26:27], v[86:87]
	s_add_u32 s57, s57, 11520
	s_cmp_ge_u32 s58, 256
	s_cbranch_scc1 .Lsc_c_itend
	v_add_u32_e32 v161, s57, v7
	v_add_u32_e32 v82, s57, v158
	ds_read_b64_tr_b16 v[14:15], v161 offset:8192
	ds_read_b64_tr_b16 v[52:53], v161 offset:8704
	ds_read_b64_tr_b16 v[56:57], v161 offset:9728
	ds_read_b64_tr_b16 v[58:59], v161 offset:9216
	v_add_u32_e32 v165, s57, v163
	ds_read_b64_tr_b16 v[88:89], v82 offset:2048
	ds_read_b64_tr_b16 v[92:93], v82 offset:2056
	v_add_u32_e32 v78, s57, v156
	v_add_u32_e32 v80, s57, v13
	v_add_u32_e32 v81, s57, v157
	v_add_u32_e32 v164, s57, v162
	ds_read_b64_tr_b16 v[96:97], v165 offset:2048
	v_cvt_pk_bf16_f32 v28, v8, v9
	v_cvt_pk_bf16_f32 v29, v10, v11
	v_cvt_pk_bf16_f32 v30, v16, v17
	v_cvt_pk_bf16_f32 v31, v18, v19
	v_cvt_pk_bf16_f32 v32, v20, v21
	v_cvt_pk_bf16_f32 v33, v22, v23
	v_cvt_pk_bf16_f32 v34, v24, v25
	v_cvt_pk_bf16_f32 v35, v26, v27
	ds_read_b64_tr_b16 v[100:101], v165 offset:2056
	s_waitcnt lgkmcnt(12)
	v_mfma_f32_16x16x32_bf16 v[104:107], v[36:39], v[28:31], 0
	s_waitcnt lgkmcnt(11)
	v_mfma_f32_16x16x32_bf16 v[112:115], v[44:47], v[28:31], 0
	s_waitcnt lgkmcnt(10)
	v_mfma_f32_16x16x32_bf16 v[104:107], v[40:43], v[32:35], v[104:107]
	s_waitcnt lgkmcnt(9)
	v_mfma_f32_16x16x32_bf16 v[112:115], v[48:51], v[32:35], v[112:115]
	s_waitcnt lgkmcnt(7)
	s_nop 2
	v_mfma_f32_16x16x16_bf16 v[104:107], v[14:15], v[60:61], v[104:107]
	ds_read_b64_tr_b16 v[90:91], v82 offset:0
	ds_read_b64_tr_b16 v[94:95], v82 offset:8
	ds_read_b64_tr_b16 v[98:99], v165 offset:0
	ds_read_b64_tr_b16 v[102:103], v165 offset:8
	s_nop 3
	v_cvt_pk_bf16_f32 v54, v104, v105
	v_cvt_pk_bf16_f32 v55, v106, v107
	s_waitcnt lgkmcnt(10)
	s_nop 0
	v_mfma_f32_16x16x16_bf16 v[108:111], v[52:53], v[54:55], 0
	s_nop 7
	v_cvt_pk_bf16_f32 v62, v108, v109
	v_cvt_pk_bf16_f32 v63, v110, v111
	s_waitcnt lgkmcnt(0)
	s_nop 0
	v_mfma_f32_16x16x32_bf16 v[112:115], v[56:59], v[60:63], v[112:115]
	ds_read_b128 v[64:67], v81 offset:0
	ds_read_b128 v[68:71], v81 offset:16
	ds_read_b128 v[72:75], v81 offset:128
	ds_read_b128 v[84:87], v81 offset:144
	v_mfma_f32_16x16x32_bf16 v[8:11], v[88:91], v[60:63], v[8:11]
	v_mfma_f32_16x16x32_bf16 v[16:19], v[92:95], v[60:63], v[16:19]
	v_mfma_f32_16x16x32_bf16 v[20:23], v[96:99], v[60:63], v[20:23]
	v_mfma_f32_16x16x32_bf16 v[24:27], v[100:103], v[60:63], v[24:27]
	v_cvt_pk_bf16_f32 v160, v112, v112
	global_store_short v159, v160, s[48:49] offset:0
	v_cvt_pk_bf16_f32 v160, v113, v113
	global_store_short v159, v160, s[48:49] offset:1024
	v_cvt_pk_bf16_f32 v160, v114, v114
	global_store_short v159, v160, s[48:49] offset:2048
	v_cvt_pk_bf16_f32 v160, v115, v115
	global_store_short v159, v160, s[48:49] offset:3072
	s_waitcnt lgkmcnt(0)
	s_add_u32 s58, s58, 1
	s_add_u32 s48, s48, 0x4000
	v_pk_mul_f32 v[8:9], v[8:9], v[64:65]
	v_pk_mul_f32 v[10:11], v[10:11], v[66:67]
	v_pk_mul_f32 v[16:17], v[16:17], v[68:69]
	v_pk_mul_f32 v[18:19], v[18:19], v[70:71]
	v_pk_mul_f32 v[20:21], v[20:21], v[72:73]
	v_pk_mul_f32 v[22:23], v[22:23], v[74:75]
	v_pk_mul_f32 v[24:25], v[24:25], v[84:85]
	v_pk_mul_f32 v[26:27], v[26:27], v[86:87]
	s_addc_u32 s49, s49, 0
	s_add_u32 s57, s57, 11520
.Lsc_c_itend:
	s_sub_u32 s56, 69120, s56

; __device__ __forceinline__ int obid() { int b = blockIdx.x; asm volatile("" : "+s"(b)); return b; }
; __device__ __forceinline__ void phase_scan2(const Params& p, int l, LAS unsigned char* lds) {
;     ...
;     for (int job = obid(); job < 256; job += gridDim.x) {
.Lsc_job_end:
	s_setprio 0
	s_add_u32 s13, s13, s62
	s_cmp_lt_u32 s13, 128
	s_cbranch_scc1 .Lsc_job
	s_waitcnt vmcnt(0) lgkmcnt(0)

; #define LAS __attribute__((address_space(3)))
; __device__ __forceinline__ int otid() { int t = threadIdx.x; asm volatile("" : "+v"(t)); return t; }
; __device__ __forceinline__ int obid() { int b = blockIdx.x; asm volatile("" : "+s"(b)); return b; }
; __device__ __forceinline__ void phase_attn(const Params& p, int l, LAS unsigned char* ldsb) {
;     ...
;     const int tid = otid(), wid = tid >> 6, lane = tid & 63, fr = lane & 15, fq = lane >> 4;
;     LAS bf16_t* Ks = (LAS bf16_t*)ldsb;
;     LAS bf16_t* Vt = (LAS bf16_t*)(ldsb + 36864);
;     LAS float* biasL = (LAS float*)(ldsb + 70656);
;     LAS bf16_t* Pw = (LAS bf16_t*)(ldsb + 72704) + wid * (16 * 168);
;     for (int item = obid(); item < 512; item += gridDim.x) {
;         const int g = item & 1, n = (item >> 1) & 31, b = item >> 6;
;         const long tokc = (long)b * SEQ + n * 128, tokp = tokc - 128;
;         for (int idx = tid; idx < 2048; idx += 512) {
;             const int key = idx >> 3, d8 = idx & 7; u32x4 v = (u32x4){0u, 0u, 0u, 0u}, kv = (u32x4){0u, 0u, 0u, 0u};
;             if (n > 0 || key >= 128) { const bf16_t* src = QKV + (size_t)(tokp + key) * 768 + 512 + g * 64 + d8 * 8; kv = *(const u32x4*)src; v = *(const u32x4*)(src + 128); }
;             *(LAS u32x4*)(Ks + key * 72 + d8 * 8) = kv;
; #pragma unroll
;             for (int e = 0; e < 8; ++e) Vt[(d8 * 8 + e) * 264 + key] = (bf16_t)((e & 1) ? (v[e >> 1] >> 16) : (v[e >> 1] & 0xffffu));
;         }
;         { const int hl = tid >> 7, d = tid & 127; int bk = d;
;           if (d >= 16) { bk = 16 + (int)(__logf((float)d * 0.0625f) * (16.f / 2.07944154168f)); bk = bk > 31 ? 31 : bk; }
;           biasL[tid] = relb[bk * 8 + g * 4 + hl]; }
;         __syncthreads();
;         const int hl = wid >> 1, hq = g * 4 + hl; const float sink = sinks[hq];
.Lat_entry:
	s_cmp_lt_u32 s5, 128
	s_cbranch_scc1 .Lat_end
	v_and_b32_e32 v0, 63, v183
	v_and_b32_e32 v1, 15, v183
	v_bfe_u32 v2, v183, 4, 2
	v_lshrrev_b32_e32 v4, 6, v183
	s_nop 0
	v_readfirstlane_b32 s44, v4
	s_nop 0
	s_lshr_b32 s45, s44, 1
	s_and_b32 s46, s44, 1
	v_readlane_b32 s0, v252, 0
	v_readlane_b32 s1, v252, 1
	s_sub_u32 s0, s0, 0xe0
	s_subb_u32 s1, s1, 0
	s_load_dwordx2 s[14:15], s[0:1], 0x38
	s_load_dwordx2 s[26:27], s[0:1], 0x40
	v_readlane_b32 s85, v243, 45
	s_nop 0
	s_lshr_b32 s85, s85, 1
	s_mov_b32 s82, 0x3e38aa3b
	v_lshrrev_b32_e32 v4, 3, v183
	v_and_b32_e32 v5, 7, v183
	v_mul_u32_u24_e32 v7, 1536, v4
	v_lshl_add_u32 v7, v5, 4, v7
	v_and_b32_e32 v6, 7, v4
	v_xor_b32_e32 v6, v6, v5
	v_lshlrev_b32_e32 v6, 4, v6
	v_lshl_add_u32 v6, v4, 7, v6
	v_bfe_u32 v3, v4, 1, 3
	v_xor_b32_e32 v3, v3, v5
	v_lshlrev_b32_e32 v3, 4, v3
	v_lshl_add_u32 v3, v4, 7, v3
	v_and_b32_e32 v8, 127, v183
	v_lshrrev_b32_e32 v4, 7, v183
	v_cvt_f32_u32_e32 v5, v8
	v_mul_f32_e32 v5, 0x3d800000, v5
	v_max_f32_e32 v5, 1.0, v5
	v_log_f32_e32 v5, v5
	s_nop 0
	v_mul_f32_e32 v5, 0x40aaaaab, v5
	v_cvt_i32_f32_e32 v5, v5
	v_add_u32_e32 v5, 16, v5
	v_min_u32_e32 v5, 31, v5
	v_cmp_gt_u32_e32 vcc, 16, v8
	s_nop 1
	v_cndmask_b32_e32 v10, v5, v8, vcc
	v_lshlrev_b32_e32 v10, 5, v10
	v_lshl_add_u32 v10, v4, 2, v10
	v_mul_u32_u24_e32 v9, 3328, v4
	v_sub_u32_e32 v5, 160, v8
	v_lshl_add_u32 v9, v5, 2, v9
	v_add_u32_e32 v9, 131072, v9
	v_add_u32_e32 v5, 96, v8
	v_subrev_u32_e32 v29, 32, v8
	v_cmp_gt_u32_e32 vcc, 32, v8
	s_nop 1
	v_cndmask_b32_e32 v5, v5, v29, vcc
	v_sub_u32_e32 v5, 160, v5
	v_mul_u32_u24_e32 v11, 3328, v4
	v_lshl_add_u32 v11, v5, 2, v11
	v_add_u32_e32 v11, 131072, v11
	v_lshlrev_b32_e32 v5, 2, v183
	v_add_u32_e32 v5, 144384, v5
	v_cmp_gt_u32_e32 vcc, 65, v8
	s_nop 1
	v_cndmask_b32_e32 v11, v5, v11, vcc
	v_bfe_u32 v4, v1, 1, 3
	v_xor_b32_e32 v4, v4, v2
	v_lshlrev_b32_e32 v4, 4, v4
	v_lshl_add_u32 v13, v1, 7, v4
	v_xor_b32_e32 v14, 64, v13
	v_and_b32_e32 v4, 3, v1
	v_mul_u32_u24_e32 v17, 832, v4
	v_and_b32_e32 v4, 12, v1
	v_lshlrev_b32_e32 v4, 2, v4
	v_sub_u32_e32 v17, v17, v4
	v_lshl_add_u32 v17, v2, 4, v17
	s_mul_i32 s51, s45, 3328
	s_add_u32 s51, s51, 131072
	v_add_u32_e32 v17, s51, v17
	v_lshrrev_b32_e32 v4, 2, v1
	v_lshl_add_u32 v4, v2, 2, v4
	v_and_b32_e32 v5, 7, v4
	v_bfe_u32 v29, v1, 1, 1
	v_and_b32_e32 v30, 1, v1
	v_lshlrev_b32_e32 v30, 3, v30
	v_lshl_add_u32 v30, v4, 7, v30
	v_add_u32_e32 v30, 32768, v30
	v_or_b32_e32 v4, 0, v29
	v_xor_b32_e32 v4, v4, v5
	v_lshl_add_u32 v19, v4, 4, v30
	v_or_b32_e32 v4, 2, v29
	v_xor_b32_e32 v4, v4, v5
	v_lshl_add_u32 v20, v4, 4, v30
	v_or_b32_e32 v4, 4, v29
	v_xor_b32_e32 v4, v4, v5
	v_lshl_add_u32 v21, v4, 4, v30
	v_or_b32_e32 v4, 6, v29
	v_xor_b32_e32 v4, v4, v5
	v_lshl_add_u32 v22, v4, 4, v30
	v_mul_u32_u24_e32 v27, 1536, v1
	v_lshl_add_u32 v27, v2, 4, v27
	v_lshlrev_b32_e32 v28, 10, v1
	v_lshl_add_u32 v28, v2, 3, v28
	v_xor_b32_e32 v29, 16, v0
	v_lshlrev_b32_e32 v29, 2, v29
	v_xor_b32_e32 v30, 32, v0
	v_lshlrev_b32_e32 v30, 2, v30
	s_sub_u32 s25, s5, 128
	s_and_b32 s2, s25, 1
	s_lshr_b32 s13, s25, 1
	s_and_b32 s13, s13, 31
	s_lshr_b32 s25, s25, 6
	s_lshl_b32 s32, s25, 12
	s_lshl_b32 s51, s13, 7
	s_add_u32 s32, s32, s51
	s_lshl_b32 s47, s2, 2
	s_add_u32 s47, s47, s45
	s_waitcnt lgkmcnt(0)
	s_mov_b32 s87, 0
; #define LAS __attribute__((address_space(3)))
; __device__ __forceinline__ int obid() { int b = blockIdx.x; asm volatile("" : "+s"(b)); return b; }
; __device__ __forceinline__ void phase_attn(const Params& p, int l, LAS unsigned char* ldsb) {
;     ...
;     for (int item = obid(); item < 512; item += gridDim.x) {
;         const int g = item & 1, n = (item >> 1) & 31, b = item >> 6;
;         const long tokc = (long)b * SEQ + n * 128, tokp = tokc - 128;
;         for (int idx = tid; idx < 2048; idx += 512) {
;             const int key = idx >> 3, d8 = idx & 7; u32x4 v = (u32x4){0u, 0u, 0u, 0u}, kv = (u32x4){0u, 0u, 0u, 0u};
;             if (n > 0 || key >= 128) { const bf16_t* src = QKV + (size_t)(tokp + key) * 768 + 512 + g * 64 + d8 * 8; kv = *(const u32x4*)src; v = *(const u32x4*)(src + 128); }
;             *(LAS u32x4*)(Ks + key * 72 + d8 * 8) = kv;
; #pragma unroll
;             for (int e = 0; e < 8; ++e) Vt[(d8 * 8 + e) * 264 + key] = (bf16_t)((e & 1) ? (v[e >> 1] >> 16) : (v[e >> 1] & 0xffffu));
;         }
;         { const int hl = tid >> 7, d = tid & 127; int bk = d;
;           if (d >= 16) { bk = 16 + (int)(__logf((float)d * 0.0625f) * (16.f / 2.07944154168f)); bk = bk > 31 ? 31 : bk; }
;           biasL[tid] = relb[bk * 8 + g * 4 + hl]; }
;         __syncthreads();
;         const int hl = wid >> 1, hq = g * 4 + hl; const float sink = sinks[hq];
;         for (int rt = 0; rt < 4; ++rt) {
;             const int q0 = (wid & 1) * 64 + rt * 16, kstart = q0 < 96 ? q0 : 96;
;             bf16x8 qa0, qa1; { const bf16_t* qp = QKV + (size_t)(tokc + q0 + fr) * 768 + hq * 64 + fq * 8; qa0 = *(const bf16x8*)qp; qa1 = *(const bf16x8*)(qp + 32); }
.Lat_again:
	s_lshl_b32 s51, s2, 4
	v_add_u32_e32 v4, s51, v10
	global_load_dword v33, v4, s[14:15]
	s_lshl_b32 s51, s85, 3
	s_add_u32 s51, s51, s47
	s_lshl_b32 s51, s51, 2
	s_add_u32 s36, s26, s51
	s_addc_u32 s37, s27, 0
	s_load_dword s83, s[36:37], 0x0
	s_mul_i32 s51, s32, 1536
	s_lshl_b32 s81, s2, 7
	s_add_u32 s51, s51, s81
	s_add_u32 s51, s51, 1024
	s_add_u32 s36, s74, s51
	s_addc_u32 s37, s75, 0
	s_add_u32 s38, s36, 12582912
	s_addc_u32 s39, s37, 0
	v_add_u32_e32 v15, 65536, v3
	v_add_u32_e32 v16, 65536, v6
	s_cmp_eq_u32 s13, 0
	s_nop 0
	s_cbranch_scc1 .Lat_stage_n0
	s_sub_u32 s36, s36, 196608
	s_subb_u32 s37, s37, 0
	s_sub_u32 s38, s38, 196608
	s_subb_u32 s39, s39, 0
	global_load_dwordx4 v[64:67], v7, s[36:37]
	global_load_dwordx4 v[68:71], v7, s[36:37] offset:256
	s_add_u32 s36, s36, 98304
	s_addc_u32 s37, s37, 0
	global_load_dwordx4 v[72:75], v7, s[38:39]
	global_load_dwordx4 v[76:79], v7, s[38:39] offset:256
	s_add_u32 s38, s38, 98304
	s_addc_u32 s39, s39, 0
	global_load_dwordx4 v[80:83], v7, s[36:37]
	global_load_dwordx4 v[84:87], v7, s[36:37] offset:256
	s_add_u32 s36, s36, 98304
	s_addc_u32 s37, s37, 0
	global_load_dwordx4 v[88:91], v7, s[38:39]
	global_load_dwordx4 v[92:95], v7, s[38:39] offset:256
	s_add_u32 s38, s38, 98304
	s_addc_u32 s39, s39, 0
	global_load_dwordx4 v[96:99], v7, s[36:37]
	global_load_dwordx4 v[100:103], v7, s[36:37] offset:256
	s_add_u32 s36, s36, 98304
	s_addc_u32 s37, s37, 0
	global_load_dwordx4 v[104:107], v7, s[38:39]
	global_load_dwordx4 v[108:111], v7, s[38:39] offset:256
	s_add_u32 s38, s38, 98304
	s_addc_u32 s39, s39, 0
	global_load_dwordx4 v[112:115], v7, s[36:37]
	global_load_dwordx4 v[116:119], v7, s[36:37] offset:256
	global_load_dwordx4 v[120:123], v7, s[38:39]
	global_load_dwordx4 v[124:127], v7, s[38:39] offset:256
	s_mov_b32 s51, 0
	s_lshr_b32 s81, s51, 2
	s_lshl_b32 s81, s81, 13
	s_and_b32 s51, s51, 3
	s_lshl_b32 s51, s51, 4
	s_add_u32 s81, s81, s51
	s_lshl_b32 s51, s46, 6
	s_add_u32 s81, s81, s51
	s_add_u32 s81, s81, s32
	s_mul_i32 s81, s81, 1536
	s_lshl_b32 s51, s47, 7
	s_add_u32 s81, s81, s51
	s_add_u32 s40, s74, s81
	s_addc_u32 s41, s75, 0
	global_load_dwordx4 v[40:43], v27, s[40:41]
	global_load_dwordx4 v[44:47], v27, s[40:41] offset:64
	s_waitcnt vmcnt(18)
	v_mul_f32_e32 v33, 0x3fb8aa3b, v33
	v_mov_b32_e32 v34, 0xff800000
	ds_write_b32 v9, v33 offset:0
	ds_write_b32 v11, v34 offset:0
	ds_write_b32 v9, v33 offset:836
	ds_write_b32 v11, v34 offset:836
	ds_write_b32 v9, v33 offset:1672
	ds_write_b32 v11, v34 offset:1672
	ds_write_b32 v9, v33 offset:2508
	ds_write_b32 v11, v34 offset:2508
	s_waitcnt vmcnt(16)
	ds_write_b128 v3, v[64:67] offset:0
	ds_write_b128 v6, v[68:71] offset:32768
	s_waitcnt vmcnt(14)
	ds_write_b128 v15, v[72:75] offset:0
	ds_write_b128 v16, v[76:79] offset:32768
	s_waitcnt vmcnt(12)
	ds_write_b128 v3, v[80:83] offset:8192
	ds_write_b128 v6, v[84:87] offset:40960
	s_waitcnt vmcnt(10)
	ds_write_b128 v15, v[88:91] offset:8192
	ds_write_b128 v16, v[92:95] offset:40960
	s_waitcnt vmcnt(8)
	ds_write_b128 v3, v[96:99] offset:16384
	ds_write_b128 v6, v[100:103] offset:49152
	s_waitcnt vmcnt(6)
	ds_write_b128 v15, v[104:107] offset:16384
	ds_write_b128 v16, v[108:111] offset:49152
	s_waitcnt vmcnt(4)
	ds_write_b128 v3, v[112:115] offset:24576
	ds_write_b128 v6, v[116:119] offset:57344
	s_waitcnt vmcnt(2)
	ds_write_b128 v15, v[120:123] offset:24576
	ds_write_b128 v16, v[124:127] offset:57344
	s_branch .Lat_staged
.Lat_stage_n0:
	global_load_dwordx4 v[96:99], v7, s[36:37]
	global_load_dwordx4 v[100:103], v7, s[36:37] offset:256
	s_add_u32 s36, s36, 98304
	s_addc_u32 s37, s37, 0
	global_load_dwordx4 v[104:107], v7, s[38:39]
	global_load_dwordx4 v[108:111], v7, s[38:39] offset:256
	s_add_u32 s38, s38, 98304
	s_addc_u32 s39, s39, 0
	global_load_dwordx4 v[112:115], v7, s[36:37]
	global_load_dwordx4 v[116:119], v7, s[36:37] offset:256
	global_load_dwordx4 v[120:123], v7, s[38:39]
	global_load_dwordx4 v[124:127], v7, s[38:39] offset:256
	s_mov_b32 s51, 0
	s_lshr_b32 s81, s51, 2
	s_lshl_b32 s81, s81, 13
	s_and_b32 s51, s51, 3
	s_lshl_b32 s51, s51, 4
	s_add_u32 s81, s81, s51
	s_lshl_b32 s51, s46, 6
	s_add_u32 s81, s81, s51
	s_add_u32 s81, s81, s32
	s_mul_i32 s81, s81, 1536
	s_lshl_b32 s51, s47, 7
	s_add_u32 s81, s81, s51
	s_add_u32 s40, s74, s81
	s_addc_u32 s41, s75, 0
	global_load_dwordx4 v[40:43], v27, s[40:41]
	global_load_dwordx4 v[44:47], v27, s[40:41] offset:64
	v_mov_b32_e32 v64, 0
	v_mov_b32_e32 v65, 0
	v_mov_b32_e32 v66, 0
	v_mov_b32_e32 v67, 0
	ds_write_b128 v3, v[64:67] offset:0
	ds_write_b128 v6, v[64:67] offset:32768
	ds_write_b128 v15, v[64:67] offset:0
	ds_write_b128 v16, v[64:67] offset:32768
	ds_write_b128 v3, v[64:67] offset:8192
	ds_write_b128 v6, v[64:67] offset:40960
	ds_write_b128 v15, v[64:67] offset:8192
	ds_write_b128 v16, v[64:67] offset:40960
	s_waitcnt vmcnt(10)
	v_mul_f32_e32 v33, 0x3fb8aa3b, v33
	v_mov_b32_e32 v34, 0xff800000
	ds_write_b32 v9, v33 offset:0
	ds_write_b32 v11, v34 offset:0
	ds_write_b32 v9, v33 offset:836
	ds_write_b32 v11, v34 offset:836
	ds_write_b32 v9, v33 offset:1672
	ds_write_b32 v11, v34 offset:1672
	ds_write_b32 v9, v33 offset:2508
	ds_write_b32 v11, v34 offset:2508
	s_waitcnt vmcnt(8)
	ds_write_b128 v3, v[96:99] offset:16384
	ds_write_b128 v6, v[100:103] offset:49152
	s_waitcnt vmcnt(6)
	ds_write_b128 v15, v[104:107] offset:16384
	ds_write_b128 v16, v[108:111] offset:49152
	s_waitcnt vmcnt(4)
	ds_write_b128 v3, v[112:115] offset:24576
	ds_write_b128 v6, v[116:119] offset:57344
	s_waitcnt vmcnt(2)
	ds_write_b128 v15, v[120:123] offset:24576
	ds_write_b128 v16, v[124:127] offset:57344

; #define LAS __attribute__((address_space(3)))
; __device__ __forceinline__ void phase_attn(const Params& p, int l, LAS unsigned char* ldsb) {
;     ...
;         for (int rt = 0; rt < 4; ++rt) {
;             const int q0 = (wid & 1) * 64 + rt * 16, kstart = q0 < 96 ? q0 : 96;
;             bf16x8 qa0, qa1; { const bf16_t* qp = QKV + (size_t)(tokc + q0 + fr) * 768 + hq * 64 + fq * 8; qa0 = *(const bf16x8*)qp; qa1 = *(const bf16x8*)(qp + 32); }
;             f32x4 S[10];
; #pragma unroll
;             for (int kt = 0; kt < 10; ++kt) {
;                 LAS const bf16_t* kp = Ks + (kstart + kt * 16 + fr) * 72 + fq * 8;
;                 const bf16x8 k0 = *(LAS const bf16x8*)kp, k1 = *(LAS const bf16x8*)(kp + 32);
;                 f32x4 z = (f32x4){0.f, 0.f, 0.f, 0.f};
;                 z = __builtin_amdgcn_mfma_f32_16x16x32_bf16(qa0, k0, z, 0, 0, 0);
;                 z = __builtin_amdgcn_mfma_f32_16x16x32_bf16(qa1, k1, z, 0, 0, 0);
;                 S[kt] = z;
;             }
;             float mx[4] = {-INFINITY, -INFINITY, -INFINITY, -INFINITY};
; #pragma unroll
;             for (int kt = 0; kt < 10; ++kt)
; #pragma unroll
;                 for (int j = 0; j < 4; ++j) {
;                     const int key = kstart + kt * 16 + fr, dist = q0 + 4 * fq + j + 128 - key;
;                     const bool ok = (dist >= 0) && (dist < 128) && (n > 0 || key >= 128);
;                     const float s = ok ? (S[kt][j] * 0.125f + biasL[hl * 128 + (dist & 127)]) : -INFINITY;
;                     S[kt][j] = s; mx[j] = fmaxf(mx[j], s);
;                 }
.Lat_rt:
	s_sleep 127
	s_and_b32 s51, s48, 3
	s_lshl_b32 s51, s51, 4
	s_lshl_b32 s49, s46, 6
	s_add_u32 s49, s49, s51
	s_min_u32 s50, s49, 96
	s_lshr_b32 s51, s48, 2
	s_lshl_b32 s81, s51, 13
	s_add_u32 s81, s81, s32
	s_add_u32 s81, s81, s49
	s_lshl_b32 s81, s81, 10
	s_lshl_b32 s84, s47, 7
	s_add_u32 s81, s81, s84
	s_add_u32 s81, s81, 0x7000000
	s_add_u32 s42, s74, s81
	s_addc_u32 s43, s75, 0
	s_lshl_b32 s51, s51, 16
	s_lshl_b32 s81, s50, 7
	s_add_u32 s51, s51, s81
	v_add_u32_e32 v15, s51, v13
	v_add_u32_e32 v16, s51, v14
	v_add_u32_e32 v23, s51, v19
	v_add_u32_e32 v24, s51, v20
	v_add_u32_e32 v25, s51, v21
	v_add_u32_e32 v26, s51, v22
	s_sub_u32 s81, s49, s50
	s_sub_u32 s81, 32, s81
	s_lshl_b32 s81, s81, 2
	v_add_u32_e32 v18, s81, v17
	s_sub_u32 s84, 128, s50
	s_lshr_b32 s84, s84, 4
	s_cmp_eq_u32 s13, 0
	s_cselect_b32 s84, s84, 0
	ds_read_b128 v[104:107], v18 offset:0
	ds_read_b128 v[108:111], v18 offset:64
	ds_read_b128 v[112:115], v18 offset:128
	ds_read_b128 v[116:119], v18 offset:192
	ds_read_b128 v[120:123], v18 offset:256
	ds_read_b128 v[124:127], v18 offset:320
	ds_read_b128 v[128:131], v18 offset:384
	ds_read_b128 v[132:135], v18 offset:448
	ds_read_b128 v[136:139], v18 offset:512
	ds_read_b128 v[140:143], v18 offset:576
	ds_read_b128 v[48:51], v15 offset:0
	ds_read_b128 v[52:55], v16 offset:0
	ds_read_b128 v[56:59], v15 offset:2048
	ds_read_b128 v[60:63], v16 offset:2048
	s_waitcnt lgkmcnt(2)
	v_mfma_f32_16x16x32_bf16 v[64:67], v[48:51], v[40:43], 0
	v_mfma_f32_16x16x32_bf16 v[64:67], v[52:55], v[44:47], v[64:67]
	ds_read_b128 v[48:51], v15 offset:4096
	ds_read_b128 v[52:55], v16 offset:4096
	s_waitcnt lgkmcnt(2)
	v_mfma_f32_16x16x32_bf16 v[68:71], v[56:59], v[40:43], 0
	v_mfma_f32_16x16x32_bf16 v[68:71], v[60:63], v[44:47], v[68:71]
	ds_read_b128 v[56:59], v15 offset:6144
	ds_read_b128 v[60:63], v16 offset:6144
	s_waitcnt lgkmcnt(2)
	v_mfma_f32_16x16x32_bf16 v[72:75], v[48:51], v[40:43], 0
	v_mfma_f32_16x16x32_bf16 v[72:75], v[52:55], v[44:47], v[72:75]
	ds_read_b128 v[48:51], v15 offset:8192
	ds_read_b128 v[52:55], v16 offset:8192
	s_waitcnt lgkmcnt(2)
	v_mfma_f32_16x16x32_bf16 v[76:79], v[56:59], v[40:43], 0
	v_mfma_f32_16x16x32_bf16 v[76:79], v[60:63], v[44:47], v[76:79]
	ds_read_b128 v[56:59], v15 offset:10240
	ds_read_b128 v[60:63], v16 offset:10240
	s_waitcnt lgkmcnt(2)
	v_mfma_f32_16x16x32_bf16 v[80:83], v[48:51], v[40:43], 0
	v_mfma_f32_16x16x32_bf16 v[80:83], v[52:55], v[44:47], v[80:83]
	ds_read_b128 v[48:51], v15 offset:12288
	ds_read_b128 v[52:55], v16 offset:12288
	s_waitcnt lgkmcnt(2)
	v_mfma_f32_16x16x32_bf16 v[84:87], v[56:59], v[40:43], 0
	v_mfma_f32_16x16x32_bf16 v[84:87], v[60:63], v[44:47], v[84:87]
	ds_read_b128 v[56:59], v15 offset:14336
	ds_read_b128 v[60:63], v16 offset:14336
	s_waitcnt lgkmcnt(2)
	v_mfma_f32_16x16x32_bf16 v[88:91], v[48:51], v[40:43], 0
	v_mfma_f32_16x16x32_bf16 v[88:91], v[52:55], v[44:47], v[88:91]
	ds_read_b128 v[48:51], v15 offset:16384
	ds_read_b128 v[52:55], v16 offset:16384
	s_waitcnt lgkmcnt(2)
	v_mfma_f32_16x16x32_bf16 v[92:95], v[56:59], v[40:43], 0
	v_mfma_f32_16x16x32_bf16 v[92:95], v[60:63], v[44:47], v[92:95]
	ds_read_b128 v[56:59], v15 offset:18432
	ds_read_b128 v[60:63], v16 offset:18432
	s_waitcnt lgkmcnt(2)
	v_mfma_f32_16x16x32_bf16 v[96:99], v[48:51], v[40:43], 0
	v_mfma_f32_16x16x32_bf16 v[96:99], v[52:55], v[44:47], v[96:99]
	s_waitcnt lgkmcnt(0)
	v_mfma_f32_16x16x32_bf16 v[100:103], v[56:59], v[40:43], 0
	v_mfma_f32_16x16x32_bf16 v[100:103], v[60:63], v[44:47], v[100:103]
	s_add_u32 s51, s48, 1
	s_min_u32 s51, s51, 7
	s_lshr_b32 s81, s51, 2
	s_lshl_b32 s81, s81, 13
	s_and_b32 s51, s51, 3
	s_lshl_b32 s51, s51, 4
	s_add_u32 s81, s81, s51
	s_lshl_b32 s51, s46, 6
	s_add_u32 s81, s81, s51
	s_add_u32 s81, s81, s32
	s_mul_i32 s81, s81, 1536
	s_lshl_b32 s51, s47, 7
	s_add_u32 s81, s81, s51
	s_add_u32 s40, s74, s81
	s_addc_u32 s41, s75, 0
	global_load_dwordx4 v[40:43], v27, s[40:41]
	global_load_dwordx4 v[44:47], v27, s[40:41] offset:64
	v_fma_f32 v64, v64, s82, v104
	v_fma_f32 v65, v65, s82, v105
	v_fma_f32 v66, v66, s82, v106
	v_fma_f32 v67, v67, s82, v107
	v_fma_f32 v68, v68, s82, v108
	v_fma_f32 v69, v69, s82, v109
	v_fma_f32 v70, v70, s82, v110
	v_fma_f32 v71, v71, s82, v111
	v_fma_f32 v72, v72, s82, v112
	v_fma_f32 v73, v73, s82, v113
	v_fma_f32 v74, v74, s82, v114
	v_fma_f32 v75, v75, s82, v115
	v_fma_f32 v76, v76, s82, v116
	v_fma_f32 v77, v77, s82, v117
	v_fma_f32 v78, v78, s82, v118
	v_fma_f32 v79, v79, s82, v119
	v_fma_f32 v80, v80, s82, v120
	v_fma_f32 v81, v81, s82, v121
	v_fma_f32 v82, v82, s82, v122
	v_fma_f32 v83, v83, s82, v123
	v_fma_f32 v84, v84, s82, v124
	v_fma_f32 v85, v85, s82, v125
	v_fma_f32 v86, v86, s82, v126
	v_fma_f32 v87, v87, s82, v127
	v_fma_f32 v88, v88, s82, v128
	v_fma_f32 v89, v89, s82, v129
	v_fma_f32 v90, v90, s82, v130
	v_fma_f32 v91, v91, s82, v131
	v_fma_f32 v92, v92, s82, v132
	v_fma_f32 v93, v93, s82, v133
	v_fma_f32 v94, v94, s82, v134
	v_fma_f32 v95, v95, s82, v135
	v_fma_f32 v96, v96, s82, v136
	v_fma_f32 v97, v97, s82, v137
	v_fma_f32 v98, v98, s82, v138
	v_fma_f32 v99, v99, s82, v139
	v_fma_f32 v100, v100, s82, v140
	v_fma_f32 v101, v101, s82, v141
	v_fma_f32 v102, v102, s82, v142
	v_fma_f32 v103, v103, s82, v143
	s_cmp_eq_u32 s84, 0
	s_nop 0
	s_cbranch_scc1 .Lat_nomask
	s_cmp_gt_u32 s84, 0
	s_cselect_b32 s86, 0xff800000, 0
	v_add_f32_e32 v64, s86, v64
	v_add_f32_e32 v65, s86, v65
	v_add_f32_e32 v66, s86, v66
	v_add_f32_e32 v67, s86, v67
	s_cmp_gt_u32 s84, 1
	s_cselect_b32 s86, 0xff800000, 0
	v_add_f32_e32 v68, s86, v68
	v_add_f32_e32 v69, s86, v69
	v_add_f32_e32 v70, s86, v70
	v_add_f32_e32 v71, s86, v71
	s_cmp_gt_u32 s84, 2
	s_cselect_b32 s86, 0xff800000, 0
	v_add_f32_e32 v72, s86, v72
	v_add_f32_e32 v73, s86, v73
	v_add_f32_e32 v74, s86, v74
	v_add_f32_e32 v75, s86, v75
	s_cmp_gt_u32 s84, 3
	s_cselect_b32 s86, 0xff800000, 0
	v_add_f32_e32 v76, s86, v76
	v_add_f32_e32 v77, s86, v77
	v_add_f32_e32 v78, s86, v78
	v_add_f32_e32 v79, s86, v79
	s_cmp_gt_u32 s84, 4
	s_cselect_b32 s86, 0xff800000, 0
	v_add_f32_e32 v80, s86, v80
	v_add_f32_e32 v81, s86, v81
	v_add_f32_e32 v82, s86, v82
	v_add_f32_e32 v83, s86, v83
	s_cmp_gt_u32 s84, 5
	s_cselect_b32 s86, 0xff800000, 0
	v_add_f32_e32 v84, s86, v84
	v_add_f32_e32 v85, s86, v85
	v_add_f32_e32 v86, s86, v86
	v_add_f32_e32 v87, s86, v87
	s_cmp_gt_u32 s84, 6
	s_cselect_b32 s86, 0xff800000, 0
	v_add_f32_e32 v88, s86, v88
	v_add_f32_e32 v89, s86, v89
	v_add_f32_e32 v90, s86, v90
	v_add_f32_e32 v91, s86, v91
	s_cmp_gt_u32 s84, 7
	s_cselect_b32 s86, 0xff800000, 0
	v_add_f32_e32 v92, s86, v92
	v_add_f32_e32 v93, s86, v93
	v_add_f32_e32 v94, s86, v94
	v_add_f32_e32 v95, s86, v95
	s_nop 1
; __device__ __forceinline__ void phase_attn(const Params& p, int l, LAS unsigned char* ldsb) {
;     ...
;             float mx[4] = {-INFINITY, -INFINITY, -INFINITY, -INFINITY};
; #pragma unroll
;             for (int kt = 0; kt < 10; ++kt)
; #pragma unroll
;                 for (int j = 0; j < 4; ++j) {
;                     const int key = kstart + kt * 16 + fr, dist = q0 + 4 * fq + j + 128 - key;
;                     const bool ok = (dist >= 0) && (dist < 128) && (n > 0 || key >= 128);
;                     const float s = ok ? (S[kt][j] * 0.125f + biasL[hl * 128 + (dist & 127)]) : -INFINITY;
;                     S[kt][j] = s; mx[j] = fmaxf(mx[j], s);
;                 }
;             float inv[4];
; #pragma unroll
;             for (int j = 0; j < 4; ++j) mx[j] = fmaxf(row16_max(mx[j]), sink);
;             float sm[4] = {0.f, 0.f, 0.f, 0.f};
; #pragma unroll
;             for (int kt = 0; kt < 10; ++kt)
; #pragma unroll
;                 for (int j = 0; j < 4; ++j) { const float e = __expf(S[kt][j] - mx[j]); S[kt][j] = e; sm[j] += e; }
; #pragma unroll
;             for (int j = 0; j < 4; ++j) inv[j] = 1.f / (row16_sum(sm[j]) + __expf(sink - mx[j]));
.Lat_nomask:
	v_max3_f32 v31, v64, v65, v66
	v_max3_f32 v31, v31, v67, v68
	v_max3_f32 v31, v31, v69, v70
	v_max3_f32 v31, v31, v71, v72
	v_max3_f32 v31, v31, v73, v74
	v_max3_f32 v31, v31, v75, v76
	v_max3_f32 v31, v31, v77, v78
	v_max3_f32 v31, v31, v79, v80
	v_max3_f32 v31, v31, v81, v82
	v_max3_f32 v31, v31, v83, v84
	v_max3_f32 v31, v31, v85, v86
	v_max3_f32 v31, v31, v87, v88
	v_max3_f32 v31, v31, v89, v90
	v_max3_f32 v31, v31, v91, v92
	v_max3_f32 v31, v31, v93, v94
	v_max3_f32 v31, v31, v95, v96
	v_max3_f32 v31, v31, v97, v98
	v_max3_f32 v31, v31, v99, v100
	v_max3_f32 v31, v31, v101, v102
	v_max_f32_e32 v31, v31, v103
	ds_bpermute_b32 v33, v29, v31
	s_waitcnt lgkmcnt(0)
	v_max_f32_e32 v31, v31, v33
	ds_bpermute_b32 v33, v30, v31
	s_waitcnt lgkmcnt(0)
	v_max_f32_e32 v31, v31, v33
	v_max_f32_e32 v31, s83, v31
	v_sub_f32_e32 v64, v64, v31
	v_sub_f32_e32 v65, v65, v31
	v_sub_f32_e32 v66, v66, v31
	v_sub_f32_e32 v67, v67, v31
	v_sub_f32_e32 v68, v68, v31
	v_sub_f32_e32 v69, v69, v31
	v_sub_f32_e32 v70, v70, v31
	v_sub_f32_e32 v71, v71, v31
	v_sub_f32_e32 v72, v72, v31
	v_sub_f32_e32 v73, v73, v31
	v_sub_f32_e32 v74, v74, v31
	v_sub_f32_e32 v75, v75, v31
	v_sub_f32_e32 v76, v76, v31
	v_sub_f32_e32 v77, v77, v31
	v_sub_f32_e32 v78, v78, v31
	v_sub_f32_e32 v79, v79, v31
	v_sub_f32_e32 v80, v80, v31
	v_sub_f32_e32 v81, v81, v31
	v_sub_f32_e32 v82, v82, v31
	v_sub_f32_e32 v83, v83, v31
	v_sub_f32_e32 v84, v84, v31
	v_sub_f32_e32 v85, v85, v31
	v_sub_f32_e32 v86, v86, v31
	v_sub_f32_e32 v87, v87, v31
	v_sub_f32_e32 v88, v88, v31
	v_sub_f32_e32 v89, v89, v31
	v_sub_f32_e32 v90, v90, v31
	v_sub_f32_e32 v91, v91, v31
	v_sub_f32_e32 v92, v92, v31
	v_sub_f32_e32 v93, v93, v31
	v_sub_f32_e32 v94, v94, v31
	v_sub_f32_e32 v95, v95, v31
	v_sub_f32_e32 v96, v96, v31
	v_sub_f32_e32 v97, v97, v31
	v_sub_f32_e32 v98, v98, v31
	v_sub_f32_e32 v99, v99, v31
	v_sub_f32_e32 v100, v100, v31
	v_sub_f32_e32 v101, v101, v31
	v_sub_f32_e32 v102, v102, v31
	v_sub_f32_e32 v103, v103, v31
	v_exp_f32_e32 v64, v64
	v_exp_f32_e32 v65, v65
	v_exp_f32_e32 v66, v66
	v_exp_f32_e32 v67, v67
	v_exp_f32_e32 v68, v68
	v_exp_f32_e32 v69, v69
	v_exp_f32_e32 v70, v70
	v_exp_f32_e32 v71, v71
	v_exp_f32_e32 v72, v72
	v_exp_f32_e32 v73, v73
	v_exp_f32_e32 v74, v74
	v_exp_f32_e32 v75, v75
	v_exp_f32_e32 v76, v76
	v_exp_f32_e32 v77, v77
	v_exp_f32_e32 v78, v78
	v_exp_f32_e32 v79, v79
	v_exp_f32_e32 v80, v80
	v_exp_f32_e32 v81, v81
	v_exp_f32_e32 v82, v82
	v_exp_f32_e32 v83, v83
	v_exp_f32_e32 v84, v84
	v_exp_f32_e32 v85, v85
	v_exp_f32_e32 v86, v86
	v_exp_f32_e32 v87, v87
	v_exp_f32_e32 v88, v88
	v_exp_f32_e32 v89, v89
	v_exp_f32_e32 v90, v90
	v_exp_f32_e32 v91, v91
	v_exp_f32_e32 v92, v92
	v_exp_f32_e32 v93, v93
	v_exp_f32_e32 v94, v94
	v_exp_f32_e32 v95, v95
	v_exp_f32_e32 v96, v96
	v_exp_f32_e32 v97, v97
	v_exp_f32_e32 v98, v98
	v_exp_f32_e32 v99, v99
	v_exp_f32_e32 v100, v100
	v_exp_f32_e32 v101, v101
	v_exp_f32_e32 v102, v102
	v_exp_f32_e32 v103, v103
	v_add_f32_e32 v32, v64, v65
	v_add_f32_e32 v32, v32, v66
	v_add_f32_e32 v32, v32, v67
	v_add_f32_e32 v32, v32, v68
	v_add_f32_e32 v32, v32, v69
	v_add_f32_e32 v32, v32, v70
	v_add_f32_e32 v32, v32, v71
	v_add_f32_e32 v32, v32, v72
	v_add_f32_e32 v32, v32, v73
	v_add_f32_e32 v32, v32, v74
	v_add_f32_e32 v32, v32, v75
	v_add_f32_e32 v32, v32, v76
	v_add_f32_e32 v32, v32, v77
	v_add_f32_e32 v32, v32, v78
	v_add_f32_e32 v32, v32, v79
	v_add_f32_e32 v32, v32, v80
	v_add_f32_e32 v32, v32, v81
	v_add_f32_e32 v32, v32, v82
	v_add_f32_e32 v32, v32, v83
	v_add_f32_e32 v32, v32, v84
	v_add_f32_e32 v32, v32, v85
	v_add_f32_e32 v32, v32, v86
	v_add_f32_e32 v32, v32, v87
	v_add_f32_e32 v32, v32, v88
	v_add_f32_e32 v32, v32, v89
	v_add_f32_e32 v32, v32, v90
	v_add_f32_e32 v32, v32, v91
	v_add_f32_e32 v32, v32, v92
	v_add_f32_e32 v32, v32, v93
	v_add_f32_e32 v32, v32, v94
	v_add_f32_e32 v32, v32, v95
	v_add_f32_e32 v32, v32, v96
	v_add_f32_e32 v32, v32, v97
	v_add_f32_e32 v32, v32, v98
	v_add_f32_e32 v32, v32, v99
	v_add_f32_e32 v32, v32, v100
	v_add_f32_e32 v32, v32, v101
	v_add_f32_e32 v32, v32, v102
	v_add_f32_e32 v32, v32, v103
	ds_bpermute_b32 v33, v29, v32
	s_waitcnt lgkmcnt(0)
	v_add_f32_e32 v32, v32, v33
	ds_bpermute_b32 v33, v30, v32
	s_waitcnt lgkmcnt(0)
; #define LAS __attribute__((address_space(3)))
; __device__ __forceinline__ unsigned pk_bf16(float lo, float hi) { const f32x2_t f = {lo, hi}; return __builtin_bit_cast(unsigned, __builtin_convertvector(f, bf16x2_t)); }
; __device__ __forceinline__ void phase_attn(const Params& p, int l, LAS unsigned char* ldsb) {
;     ...
;             for (int j = 0; j < 4; ++j) inv[j] = 1.f / (row16_sum(sm[j]) + __expf(sink - mx[j]));
; #pragma unroll
;             for (int kt = 0; kt < 10; ++kt)
; #pragma unroll
;                 for (int j = 0; j < 4; ++j) Pw[(4 * fq + j) * 168 + kt * 16 + fr] = (bf16_t)(pk_bf16(S[kt][j] * inv[j], 0.f) & 0xffffu);
;             asm volatile("s_waitcnt lgkmcnt(0)" ::: "memory");
;             __builtin_amdgcn_wave_barrier();
;             f32x4 O[4];
; #pragma unroll
;             for (int dt = 0; dt < 4; ++dt) O[dt] = (f32x4){0.f, 0.f, 0.f, 0.f};
; #pragma unroll
;             for (int kk = 0; kk < 5; ++kk) {
;                 const bf16x8 pa = *(LAS const bf16x8*)(Pw + fr * 168 + kk * 32 + fq * 8);
; #pragma unroll
;                 for (int dt = 0; dt < 4; ++dt) {
;                     const bf16x8 vb = *(LAS const bf16x8*)(Vt + (dt * 16 + fr) * 264 + kstart + kk * 32 + fq * 8);
;                     O[dt] = __builtin_amdgcn_mfma_f32_16x16x32_bf16(pa, vb, O[dt], 0, 0, 0);
;                 }
;             }
; #pragma unroll
;             for (int dt = 0; dt < 4; ++dt)
; #pragma unroll
;                 for (int j = 0; j < 4; ++j) ATT[(size_t)(tokc + q0 + 4 * fq + j) * 512 + hq * 64 + dt * 16 + fr] = (bf16_t)(pk_bf16(O[dt][j], 0.f) & 0xffffu);
;             asm volatile("s_waitcnt lgkmcnt(0)" ::: "memory");
;             __builtin_amdgcn_wave_barrier();
;         }
	v_add_f32_e32 v32, v32, v33
	v_sub_f32_e32 v33, s83, v31
	v_exp_f32_e32 v33, v33
	s_nop 0
	v_add_f32_e32 v32, v32, v33
	v_rcp_f32_e32 v36, v32
	s_nop 0
	v_fma_f32 v33, -v32, v36, 2.0
	v_mul_f32_e32 v36, v36, v33
	v_mul_f32_e32 v64, v36, v64
	v_mul_f32_e32 v65, v36, v65
	v_cvt_pk_bf16_f32 v144, v64, v65
	v_mul_f32_e32 v66, v36, v66
	v_mul_f32_e32 v67, v36, v67
	v_cvt_pk_bf16_f32 v145, v66, v67
	v_mul_f32_e32 v68, v36, v68
	v_mul_f32_e32 v69, v36, v69
	v_cvt_pk_bf16_f32 v146, v68, v69
	v_mul_f32_e32 v70, v36, v70
	v_mul_f32_e32 v71, v36, v71
	v_cvt_pk_bf16_f32 v147, v70, v71
	v_mul_f32_e32 v72, v36, v72
	v_mul_f32_e32 v73, v36, v73
	v_cvt_pk_bf16_f32 v148, v72, v73
	v_mul_f32_e32 v74, v36, v74
	v_mul_f32_e32 v75, v36, v75
	v_cvt_pk_bf16_f32 v149, v74, v75
	v_mul_f32_e32 v76, v36, v76
	v_mul_f32_e32 v77, v36, v77
	v_cvt_pk_bf16_f32 v150, v76, v77
	v_mul_f32_e32 v78, v36, v78
	v_mul_f32_e32 v79, v36, v79
	v_cvt_pk_bf16_f32 v151, v78, v79
	v_mul_f32_e32 v80, v36, v80
	v_mul_f32_e32 v81, v36, v81
	v_cvt_pk_bf16_f32 v152, v80, v81
	v_mul_f32_e32 v82, v36, v82
	v_mul_f32_e32 v83, v36, v83
	v_cvt_pk_bf16_f32 v153, v82, v83
	v_mul_f32_e32 v84, v36, v84
	v_mul_f32_e32 v85, v36, v85
	v_cvt_pk_bf16_f32 v154, v84, v85
	v_mul_f32_e32 v86, v36, v86
	v_mul_f32_e32 v87, v36, v87
	v_cvt_pk_bf16_f32 v155, v86, v87
	v_mul_f32_e32 v88, v36, v88
	v_mul_f32_e32 v89, v36, v89
	v_cvt_pk_bf16_f32 v156, v88, v89
	v_mul_f32_e32 v90, v36, v90
	v_mul_f32_e32 v91, v36, v91
	v_cvt_pk_bf16_f32 v157, v90, v91
	v_mul_f32_e32 v92, v36, v92
	v_mul_f32_e32 v93, v36, v93
	v_cvt_pk_bf16_f32 v158, v92, v93
	v_mul_f32_e32 v94, v36, v94
	v_mul_f32_e32 v95, v36, v95
	v_cvt_pk_bf16_f32 v159, v94, v95
	v_mul_f32_e32 v96, v36, v96
	v_mul_f32_e32 v97, v36, v97
	v_cvt_pk_bf16_f32 v160, v96, v97
	v_mul_f32_e32 v98, v36, v98
	v_mul_f32_e32 v99, v36, v99
	v_cvt_pk_bf16_f32 v161, v98, v99
	v_mul_f32_e32 v100, v36, v100
	v_mul_f32_e32 v101, v36, v101
	v_cvt_pk_bf16_f32 v162, v100, v101
	v_mul_f32_e32 v102, v36, v102
	v_mul_f32_e32 v103, v36, v103
	v_cvt_pk_bf16_f32 v163, v102, v103
	ds_read_b64_tr_b16 v[200:201], v23 offset:0
	ds_read_b64_tr_b16 v[202:203], v23 offset:2048
	ds_read_b64_tr_b16 v[204:205], v24 offset:0
	ds_read_b64_tr_b16 v[206:207], v24 offset:2048
	ds_read_b64_tr_b16 v[208:209], v25 offset:0
	ds_read_b64_tr_b16 v[210:211], v25 offset:2048
	ds_read_b64_tr_b16 v[220:221], v26 offset:0
	ds_read_b64_tr_b16 v[222:223], v26 offset:2048
	ds_read_b64_tr_b16 v[224:225], v23 offset:4096
	ds_read_b64_tr_b16 v[226:227], v23 offset:6144
	ds_read_b64_tr_b16 v[228:229], v24 offset:4096
	ds_read_b64_tr_b16 v[230:231], v24 offset:6144
	ds_read_b64_tr_b16 v[232:233], v25 offset:4096
	ds_read_b64_tr_b16 v[234:235], v25 offset:6144
	ds_read_b64_tr_b16 v[236:237], v26 offset:4096
	ds_read_b64_tr_b16 v[238:239], v26 offset:6144
	s_waitcnt lgkmcnt(14)
	v_mfma_f32_16x16x32_bf16 v[164:167], v[200:203], v[144:147], 0
	s_waitcnt lgkmcnt(12)
	v_mfma_f32_16x16x32_bf16 v[168:171], v[204:207], v[144:147], 0
	s_waitcnt lgkmcnt(10)
	v_mfma_f32_16x16x32_bf16 v[172:175], v[208:211], v[144:147], 0
	s_waitcnt lgkmcnt(8)
	v_mfma_f32_16x16x32_bf16 v[196:199], v[220:223], v[144:147], 0
	ds_read_b64_tr_b16 v[200:201], v23 offset:8192
	ds_read_b64_tr_b16 v[202:203], v23 offset:10240
	ds_read_b64_tr_b16 v[204:205], v24 offset:8192
	ds_read_b64_tr_b16 v[206:207], v24 offset:10240
	ds_read_b64_tr_b16 v[208:209], v25 offset:8192
	ds_read_b64_tr_b16 v[210:211], v25 offset:10240
	ds_read_b64_tr_b16 v[220:221], v26 offset:8192
	ds_read_b64_tr_b16 v[222:223], v26 offset:10240
	s_waitcnt lgkmcnt(14)
	v_mfma_f32_16x16x32_bf16 v[164:167], v[224:227], v[148:151], v[164:167]
	s_waitcnt lgkmcnt(12)
	v_mfma_f32_16x16x32_bf16 v[168:171], v[228:231], v[148:151], v[168:171]
	s_waitcnt lgkmcnt(10)
	v_mfma_f32_16x16x32_bf16 v[172:175], v[232:235], v[148:151], v[172:175]
	s_waitcnt lgkmcnt(8)
	v_mfma_f32_16x16x32_bf16 v[196:199], v[236:239], v[148:151], v[196:199]
	ds_read_b64_tr_b16 v[224:225], v23 offset:12288
	ds_read_b64_tr_b16 v[226:227], v23 offset:14336
	ds_read_b64_tr_b16 v[228:229], v24 offset:12288
	ds_read_b64_tr_b16 v[230:231], v24 offset:14336
	ds_read_b64_tr_b16 v[232:233], v25 offset:12288
	ds_read_b64_tr_b16 v[234:235], v25 offset:14336
	ds_read_b64_tr_b16 v[236:237], v26 offset:12288
	ds_read_b64_tr_b16 v[238:239], v26 offset:14336
	s_waitcnt lgkmcnt(14)
	v_mfma_f32_16x16x32_bf16 v[164:167], v[200:203], v[152:155], v[164:167]
	s_waitcnt lgkmcnt(12)
	v_mfma_f32_16x16x32_bf16 v[168:171], v[204:207], v[152:155], v[168:171]
	s_waitcnt lgkmcnt(10)
	v_mfma_f32_16x16x32_bf16 v[172:175], v[208:211], v[152:155], v[172:175]
	s_waitcnt lgkmcnt(8)
	v_mfma_f32_16x16x32_bf16 v[196:199], v[220:223], v[152:155], v[196:199]
	ds_read_b64_tr_b16 v[200:201], v23 offset:16384
	ds_read_b64_tr_b16 v[202:203], v23 offset:18432
	ds_read_b64_tr_b16 v[204:205], v24 offset:16384
	ds_read_b64_tr_b16 v[206:207], v24 offset:18432
	ds_read_b64_tr_b16 v[208:209], v25 offset:16384
	ds_read_b64_tr_b16 v[210:211], v25 offset:18432
	ds_read_b64_tr_b16 v[220:221], v26 offset:16384
	ds_read_b64_tr_b16 v[222:223], v26 offset:18432
	s_waitcnt lgkmcnt(14)
	v_mfma_f32_16x16x32_bf16 v[164:167], v[224:227], v[156:159], v[164:167]
	s_waitcnt lgkmcnt(12)
	v_mfma_f32_16x16x32_bf16 v[168:171], v[228:231], v[156:159], v[168:171]
	s_waitcnt lgkmcnt(10)
	v_mfma_f32_16x16x32_bf16 v[172:175], v[232:235], v[156:159], v[172:175]
	s_waitcnt lgkmcnt(8)
	v_mfma_f32_16x16x32_bf16 v[196:199], v[236:239], v[156:159], v[196:199]
	s_waitcnt lgkmcnt(6)
	v_mfma_f32_16x16x32_bf16 v[164:167], v[200:203], v[160:163], v[164:167]
	s_waitcnt lgkmcnt(4)
	v_mfma_f32_16x16x32_bf16 v[168:171], v[204:207], v[160:163], v[168:171]
	s_waitcnt lgkmcnt(2)
	v_mfma_f32_16x16x32_bf16 v[172:175], v[208:211], v[160:163], v[172:175]
	s_waitcnt lgkmcnt(0)
	v_mfma_f32_16x16x32_bf16 v[196:199], v[220:223], v[160:163], v[196:199]
	s_nop 1
	v_cvt_pk_bf16_f32 v38, v164, v165
	v_cvt_pk_bf16_f32 v39, v166, v167
	global_store_dwordx2 v28, v[38:39], s[42:43] offset:0
	v_cvt_pk_bf16_f32 v38, v168, v169
	v_cvt_pk_bf16_f32 v39, v170, v171
	global_store_dwordx2 v28, v[38:39], s[42:43] offset:32
	v_cvt_pk_bf16_f32 v38, v172, v173
	v_cvt_pk_bf16_f32 v39, v174, v175
	global_store_dwordx2 v28, v[38:39], s[42:43] offset:64
	v_cvt_pk_bf16_f32 v38, v196, v197
	v_cvt_pk_bf16_f32 v39, v198, v199
	global_store_dwordx2 v28, v[38:39], s[42:43] offset:96
	s_waitcnt vmcnt(4)
	s_add_u32 s48, s48, 1
	s_cmp_lt_u32 s48, 8
	s_cbranch_scc1 .Lat_rt
	s_add_u32 s87, s87, 1
	s_cmp_lt_u32 s87, 2
	s_cbranch_scc0 .Lat_end
	s_xor_b32 s32, s32, 16384
	s_waitcnt lgkmcnt(0)
	s_barrier
	s_branch .Lat_again
